# hand-written residual epilogues (G5, G8) and gate-merge epilogue (G4): all loads of the tile issued up front, packed math, original fma order
# speedup vs baseline: 1.0010x; 1.0010x over previous
; __device__ __forceinline__ u32x4 pack8(const f32x4 a, const f32x4 b) { u32x4 w; w.x = pk2(a[0], a[1]); w.y = pk2(a[2], a[3]); w.z = pk2(b[0], b[1]); w.w = pk2(b[2], b[3]); return w; }
; __device__ __forceinline__ void unpack8(const u32x4 w, f32x4& a, f32x4& b) { a[0] = bflo(w.x); a[1] = bfhi(w.x); a[2] = bflo(w.y); a[3] = bfhi(w.y); b[0] = bflo(w.z); b[1] = bfhi(w.z); b[2] = bflo(w.w); b[3] = bfhi(w.w); }
; __device__ __forceinline__ f32x4 vsig(const f32x4 x) {
;     const f32x4 t = x * (-1.4426950409f); f32x4 d;
; #pragma unroll
;     for (int e = 0; e < 4; ++e) d[e] = __builtin_amdgcn_exp2f(t[e]);
;     d = d + 1.0f; f32x4 r;
; #pragma unroll
;     for (int e = 0; e < 4; ++e) r[e] = __builtin_amdgcn_rcpf(d[e]);
;     return r;
; }
;     __device__ __forceinline__ bool operator()(EPI_ARGS) const {
; #pragma unroll
;         for (int ai = 0; ai < 2; ++ai) {
;             u32x4 ra[4], rc[4];
; #pragma unroll
;             for (int m = 0; m < 4; ++m) { const size_t off = ((size_t)u.pm * 256 + ROWLOC(ai, m)) * D + u.pn * 128 + 32 * wc + 8 * fq; ra[m] = *(const u32x4*)(yr + off); rc[m] = *(const u32x4*)(yc + off); }
; #pragma unroll
;             for (int m = 0; m < 4; ++m) {
;                 const size_t off = ((size_t)u.pm * 256 + ROWLOC(ai, m)) * D + u.pn * 128 + 32 * wc + 8 * fq;
;                 f32x4 a0, a1, c0, c1; unpack8(ra[m], a0, a1); unpack8(rc[m], c0, c1);
;                 const f32x4 o0 = vsig(acc[ai][0][m][0]) * a0 + vsig(acc[ai][1][m][0]) * c0, o1 = vsig(acc[ai][0][m][1]) * a1 + vsig(acc[ai][1][m][1]) * c1;
;                 *(u32x4*)(yr + off) = pack8(o0, o1);
;             }
;             asm volatile("" ::: "memory");
;         }
.LBB0_1283:
	s_lshl_b32 s38, s22, 19
	s_lshl_b32 s40, s60, 8
	s_add_i32 s38, s38, s40
	s_lshl_b32 s40, s16, 1
	s_add_i32 s38, s38, s40
	v_add_u32_e32 v161, s50, v154
	v_lshlrev_b32_e32 v177, 4, v155
	v_lshl_add_u32 v161, v161, 11, v177
	v_add_u32_e32 v161, s38, v161
	v_mov_b32_e32 v224, 0xbfb8aa3b
	v_mov_b32_e32 v225, 0xbfb8aa3b
	global_load_dwordx4 v[128:131], v161, s[12:13]
	global_load_dwordx4 v[132:135], v161, s[14:15]
	v_add_u32_e32 v177, 0x8000, v161
	global_load_dwordx4 v[140:143], v177, s[12:13]
	global_load_dwordx4 v[144:147], v177, s[14:15]
	v_add_u32_e32 v177, 0x10000, v161
	global_load_dwordx4 v[148:151], v177, s[12:13]
	global_load_dwordx4 v[164:167], v177, s[14:15]
	v_add_u32_e32 v177, 0x18000, v161
	global_load_dwordx4 v[168:171], v177, s[12:13]
	global_load_dwordx4 v[172:175], v177, s[14:15]
	v_add_u32_e32 v177, 0x40000, v161
	global_load_dwordx4 v[180:183], v177, s[12:13]
	global_load_dwordx4 v[184:187], v177, s[14:15]
	v_add_u32_e32 v177, 0x48000, v161
	global_load_dwordx4 v[188:191], v177, s[12:13]
	global_load_dwordx4 v[192:195], v177, s[14:15]
	v_add_u32_e32 v177, 0x50000, v161
	global_load_dwordx4 v[196:199], v177, s[12:13]
	global_load_dwordx4 v[200:203], v177, s[14:15]
	v_add_u32_e32 v177, 0x58000, v161
	global_load_dwordx4 v[204:207], v177, s[12:13]
	global_load_dwordx4 v[208:211], v177, s[14:15]
	v_pk_mul_f32 v[124:125], v[124:125], v[224:225]
	v_pk_mul_f32 v[126:127], v[126:127], v[224:225]
	v_pk_mul_f32 v[116:117], v[116:117], v[224:225]
	v_pk_mul_f32 v[118:119], v[118:119], v[224:225]
	v_pk_mul_f32 v[120:121], v[120:121], v[224:225]
	v_pk_mul_f32 v[122:123], v[122:123], v[224:225]
	v_pk_mul_f32 v[112:113], v[112:113], v[224:225]
	v_pk_mul_f32 v[114:115], v[114:115], v[224:225]
	v_exp_f32_e32 v124, v124
	v_exp_f32_e32 v125, v125
	v_exp_f32_e32 v126, v126
	v_exp_f32_e32 v127, v127
	v_exp_f32_e32 v116, v116
	v_exp_f32_e32 v117, v117
	v_exp_f32_e32 v118, v118
	v_exp_f32_e32 v119, v119
	v_exp_f32_e32 v120, v120
	v_exp_f32_e32 v121, v121
	v_exp_f32_e32 v122, v122
	v_exp_f32_e32 v123, v123
	v_exp_f32_e32 v112, v112
	v_exp_f32_e32 v113, v113
	v_exp_f32_e32 v114, v114
	v_exp_f32_e32 v115, v115
	v_pk_add_f32 v[124:125], v[124:125], 1.0 op_sel_hi:[1,0]
	v_pk_add_f32 v[126:127], v[126:127], 1.0 op_sel_hi:[1,0]
	v_pk_add_f32 v[116:117], v[116:117], 1.0 op_sel_hi:[1,0]
	v_pk_add_f32 v[118:119], v[118:119], 1.0 op_sel_hi:[1,0]
	v_pk_add_f32 v[120:121], v[120:121], 1.0 op_sel_hi:[1,0]
	v_pk_add_f32 v[122:123], v[122:123], 1.0 op_sel_hi:[1,0]
	v_pk_add_f32 v[112:113], v[112:113], 1.0 op_sel_hi:[1,0]
	v_pk_add_f32 v[114:115], v[114:115], 1.0 op_sel_hi:[1,0]
	v_rcp_f32_e32 v124, v124
	v_rcp_f32_e32 v125, v125
	v_rcp_f32_e32 v126, v126
	v_rcp_f32_e32 v127, v127
	v_rcp_f32_e32 v116, v116
	v_rcp_f32_e32 v117, v117
	v_rcp_f32_e32 v118, v118
	v_rcp_f32_e32 v119, v119
	v_rcp_f32_e32 v120, v120
	v_rcp_f32_e32 v121, v121
	v_rcp_f32_e32 v122, v122
	v_rcp_f32_e32 v123, v123
	v_rcp_f32_e32 v112, v112
	v_rcp_f32_e32 v113, v113
	v_rcp_f32_e32 v114, v114
	v_rcp_f32_e32 v115, v115
	s_waitcnt vmcnt(14)
	v_lshlrev_b32_e32 v162, 16, v128
	v_and_b32_e32 v163, 0xffff0000, v128
	v_lshlrev_b32_e32 v216, 16, v132
	v_and_b32_e32 v217, 0xffff0000, v132
	v_lshlrev_b32_e32 v178, 16, v129
	v_and_b32_e32 v179, 0xffff0000, v129
	v_lshlrev_b32_e32 v218, 16, v133
	v_and_b32_e32 v219, 0xffff0000, v133
	v_lshlrev_b32_e32 v212, 16, v130
	v_and_b32_e32 v213, 0xffff0000, v130
	v_lshlrev_b32_e32 v220, 16, v134
	v_and_b32_e32 v221, 0xffff0000, v134
	v_lshlrev_b32_e32 v214, 16, v131
	v_and_b32_e32 v215, 0xffff0000, v131
	v_lshlrev_b32_e32 v222, 16, v135
	v_and_b32_e32 v223, 0xffff0000, v135
	v_pk_mul_f32 v[216:217], v[120:121], v[216:217]
	v_pk_mul_f32 v[218:219], v[122:123], v[218:219]
	v_pk_fma_f32 v[162:163], v[124:125], v[162:163], v[216:217]
	v_pk_fma_f32 v[178:179], v[126:127], v[178:179], v[218:219]
	v_pk_mul_f32 v[220:221], v[112:113], v[220:221]
	v_pk_mul_f32 v[222:223], v[114:115], v[222:223]
	v_pk_fma_f32 v[212:213], v[116:117], v[212:213], v[220:221]
	v_pk_fma_f32 v[214:215], v[118:119], v[214:215], v[222:223]
	v_cvt_pk_bf16_f32 v128, v162, v163
	v_cvt_pk_bf16_f32 v129, v178, v179
	v_cvt_pk_bf16_f32 v130, v212, v213
	v_cvt_pk_bf16_f32 v131, v214, v215
	global_store_dwordx4 v161, v[128:131], s[12:13]
	v_pk_mul_f32 v[108:109], v[108:109], v[224:225]
	v_pk_mul_f32 v[110:111], v[110:111], v[224:225]
	v_pk_mul_f32 v[100:101], v[100:101], v[224:225]
	v_pk_mul_f32 v[102:103], v[102:103], v[224:225]
	v_pk_mul_f32 v[104:105], v[104:105], v[224:225]
	v_pk_mul_f32 v[106:107], v[106:107], v[224:225]
	v_pk_mul_f32 v[96:97], v[96:97], v[224:225]
	v_pk_mul_f32 v[98:99], v[98:99], v[224:225]
	v_exp_f32_e32 v108, v108
	v_exp_f32_e32 v109, v109
	v_exp_f32_e32 v110, v110
	v_exp_f32_e32 v111, v111
	v_exp_f32_e32 v100, v100
	v_exp_f32_e32 v101, v101
	v_exp_f32_e32 v102, v102
	v_exp_f32_e32 v103, v103
	v_exp_f32_e32 v104, v104
	v_exp_f32_e32 v105, v105
	v_exp_f32_e32 v106, v106
	v_exp_f32_e32 v107, v107
	v_exp_f32_e32 v96, v96
	v_exp_f32_e32 v97, v97
	v_exp_f32_e32 v98, v98
	v_exp_f32_e32 v99, v99
	v_pk_add_f32 v[108:109], v[108:109], 1.0 op_sel_hi:[1,0]
	v_pk_add_f32 v[110:111], v[110:111], 1.0 op_sel_hi:[1,0]
	v_pk_add_f32 v[100:101], v[100:101], 1.0 op_sel_hi:[1,0]
	v_pk_add_f32 v[102:103], v[102:103], 1.0 op_sel_hi:[1,0]
	v_pk_add_f32 v[104:105], v[104:105], 1.0 op_sel_hi:[1,0]
	v_pk_add_f32 v[106:107], v[106:107], 1.0 op_sel_hi:[1,0]
	v_pk_add_f32 v[96:97], v[96:97], 1.0 op_sel_hi:[1,0]
	v_pk_add_f32 v[98:99], v[98:99], 1.0 op_sel_hi:[1,0]
	v_rcp_f32_e32 v108, v108
	v_rcp_f32_e32 v109, v109
	v_rcp_f32_e32 v110, v110
	v_rcp_f32_e32 v111, v111
	v_rcp_f32_e32 v100, v100
	v_rcp_f32_e32 v101, v101
	v_rcp_f32_e32 v102, v102
	v_rcp_f32_e32 v103, v103
	v_rcp_f32_e32 v104, v104
	v_rcp_f32_e32 v105, v105
	v_rcp_f32_e32 v106, v106
	v_rcp_f32_e32 v107, v107
	v_rcp_f32_e32 v96, v96
	v_rcp_f32_e32 v97, v97
	v_rcp_f32_e32 v98, v98
	v_rcp_f32_e32 v99, v99
	s_waitcnt vmcnt(13)
; __device__ __forceinline__ u32x4 pack8(const f32x4 a, const f32x4 b) { u32x4 w; w.x = pk2(a[0], a[1]); w.y = pk2(a[2], a[3]); w.z = pk2(b[0], b[1]); w.w = pk2(b[2], b[3]); return w; }
; __device__ __forceinline__ void unpack8(const u32x4 w, f32x4& a, f32x4& b) { a[0] = bflo(w.x); a[1] = bfhi(w.x); a[2] = bflo(w.y); a[3] = bfhi(w.y); b[0] = bflo(w.z); b[1] = bfhi(w.z); b[2] = bflo(w.w); b[3] = bfhi(w.w); }
;     __device__ __forceinline__ bool operator()(EPI_ARGS) const {
;     ...
;             for (int m = 0; m < 4; ++m) { const size_t off = ((size_t)u.pm * 256 + ROWLOC(ai, m)) * D + u.pn * 128 + 32 * wc + 8 * fq; ra[m] = *(const u32x4*)(yr + off); rc[m] = *(const u32x4*)(yc + off); }
; #pragma unroll
;             for (int m = 0; m < 4; ++m) {
;                 const size_t off = ((size_t)u.pm * 256 + ROWLOC(ai, m)) * D + u.pn * 128 + 32 * wc + 8 * fq;
;                 f32x4 a0, a1, c0, c1; unpack8(ra[m], a0, a1); unpack8(rc[m], c0, c1);
;                 const f32x4 o0 = vsig(acc[ai][0][m][0]) * a0 + vsig(acc[ai][1][m][0]) * c0, o1 = vsig(acc[ai][0][m][1]) * a1 + vsig(acc[ai][1][m][1]) * c1;
;                 *(u32x4*)(yr + off) = pack8(o0, o1);
;             }
	v_lshlrev_b32_e32 v162, 16, v140
	v_and_b32_e32 v163, 0xffff0000, v140
	v_lshlrev_b32_e32 v216, 16, v144
	v_and_b32_e32 v217, 0xffff0000, v144
	v_lshlrev_b32_e32 v178, 16, v141
	v_and_b32_e32 v179, 0xffff0000, v141
	v_lshlrev_b32_e32 v218, 16, v145
	v_and_b32_e32 v219, 0xffff0000, v145
	v_lshlrev_b32_e32 v212, 16, v142
	v_and_b32_e32 v213, 0xffff0000, v142
	v_lshlrev_b32_e32 v220, 16, v146
	v_and_b32_e32 v221, 0xffff0000, v146
	v_lshlrev_b32_e32 v214, 16, v143
	v_and_b32_e32 v215, 0xffff0000, v143
	v_lshlrev_b32_e32 v222, 16, v147
	v_and_b32_e32 v223, 0xffff0000, v147
	v_pk_mul_f32 v[216:217], v[104:105], v[216:217]
	v_pk_mul_f32 v[218:219], v[106:107], v[218:219]
	v_pk_fma_f32 v[162:163], v[108:109], v[162:163], v[216:217]
	v_pk_fma_f32 v[178:179], v[110:111], v[178:179], v[218:219]
	v_pk_mul_f32 v[220:221], v[96:97], v[220:221]
	v_pk_mul_f32 v[222:223], v[98:99], v[222:223]
	v_pk_fma_f32 v[212:213], v[100:101], v[212:213], v[220:221]
	v_pk_fma_f32 v[214:215], v[102:103], v[214:215], v[222:223]
	v_cvt_pk_bf16_f32 v140, v162, v163
	v_cvt_pk_bf16_f32 v141, v178, v179
	v_cvt_pk_bf16_f32 v142, v212, v213
	v_cvt_pk_bf16_f32 v143, v214, v215
	v_add_u32_e32 v177, 0x8000, v161
	global_store_dwordx4 v177, v[140:143], s[12:13]
	v_pk_mul_f32 v[92:93], v[92:93], v[224:225]
	v_pk_mul_f32 v[94:95], v[94:95], v[224:225]
	v_pk_mul_f32 v[84:85], v[84:85], v[224:225]
	v_pk_mul_f32 v[86:87], v[86:87], v[224:225]
	v_pk_mul_f32 v[88:89], v[88:89], v[224:225]
	v_pk_mul_f32 v[90:91], v[90:91], v[224:225]
	v_pk_mul_f32 v[80:81], v[80:81], v[224:225]
	v_pk_mul_f32 v[82:83], v[82:83], v[224:225]
	v_exp_f32_e32 v92, v92
	v_exp_f32_e32 v93, v93
	v_exp_f32_e32 v94, v94
	v_exp_f32_e32 v95, v95
	v_exp_f32_e32 v84, v84
	v_exp_f32_e32 v85, v85
	v_exp_f32_e32 v86, v86
	v_exp_f32_e32 v87, v87
	v_exp_f32_e32 v88, v88
	v_exp_f32_e32 v89, v89
	v_exp_f32_e32 v90, v90
	v_exp_f32_e32 v91, v91
	v_exp_f32_e32 v80, v80
	v_exp_f32_e32 v81, v81
	v_exp_f32_e32 v82, v82
	v_exp_f32_e32 v83, v83
	v_pk_add_f32 v[92:93], v[92:93], 1.0 op_sel_hi:[1,0]
	v_pk_add_f32 v[94:95], v[94:95], 1.0 op_sel_hi:[1,0]
	v_pk_add_f32 v[84:85], v[84:85], 1.0 op_sel_hi:[1,0]
	v_pk_add_f32 v[86:87], v[86:87], 1.0 op_sel_hi:[1,0]
	v_pk_add_f32 v[88:89], v[88:89], 1.0 op_sel_hi:[1,0]
	v_pk_add_f32 v[90:91], v[90:91], 1.0 op_sel_hi:[1,0]
	v_pk_add_f32 v[80:81], v[80:81], 1.0 op_sel_hi:[1,0]
	v_pk_add_f32 v[82:83], v[82:83], 1.0 op_sel_hi:[1,0]
	v_rcp_f32_e32 v92, v92
	v_rcp_f32_e32 v93, v93
	v_rcp_f32_e32 v94, v94
	v_rcp_f32_e32 v95, v95
	v_rcp_f32_e32 v84, v84
	v_rcp_f32_e32 v85, v85
	v_rcp_f32_e32 v86, v86
	v_rcp_f32_e32 v87, v87
	v_rcp_f32_e32 v88, v88
	v_rcp_f32_e32 v89, v89
	v_rcp_f32_e32 v90, v90
	v_rcp_f32_e32 v91, v91
	v_rcp_f32_e32 v80, v80
	v_rcp_f32_e32 v81, v81
	v_rcp_f32_e32 v82, v82
	v_rcp_f32_e32 v83, v83
	s_waitcnt vmcnt(12)
	v_lshlrev_b32_e32 v162, 16, v148
	v_and_b32_e32 v163, 0xffff0000, v148
	v_lshlrev_b32_e32 v216, 16, v164
	v_and_b32_e32 v217, 0xffff0000, v164
	v_lshlrev_b32_e32 v178, 16, v149
	v_and_b32_e32 v179, 0xffff0000, v149
	v_lshlrev_b32_e32 v218, 16, v165
	v_and_b32_e32 v219, 0xffff0000, v165
	v_lshlrev_b32_e32 v212, 16, v150
	v_and_b32_e32 v213, 0xffff0000, v150
	v_lshlrev_b32_e32 v220, 16, v166
	v_and_b32_e32 v221, 0xffff0000, v166
	v_lshlrev_b32_e32 v214, 16, v151
	v_and_b32_e32 v215, 0xffff0000, v151
	v_lshlrev_b32_e32 v222, 16, v167
	v_and_b32_e32 v223, 0xffff0000, v167
	v_pk_mul_f32 v[216:217], v[88:89], v[216:217]
	v_pk_mul_f32 v[218:219], v[90:91], v[218:219]
	v_pk_fma_f32 v[162:163], v[92:93], v[162:163], v[216:217]
	v_pk_fma_f32 v[178:179], v[94:95], v[178:179], v[218:219]
	v_pk_mul_f32 v[220:221], v[80:81], v[220:221]
	v_pk_mul_f32 v[222:223], v[82:83], v[222:223]
	v_pk_fma_f32 v[212:213], v[84:85], v[212:213], v[220:221]
	v_pk_fma_f32 v[214:215], v[86:87], v[214:215], v[222:223]
	v_cvt_pk_bf16_f32 v148, v162, v163
	v_cvt_pk_bf16_f32 v149, v178, v179
	v_cvt_pk_bf16_f32 v150, v212, v213
	v_cvt_pk_bf16_f32 v151, v214, v215
	v_add_u32_e32 v177, 0x10000, v161
	global_store_dwordx4 v177, v[148:151], s[12:13]
	v_pk_mul_f32 v[76:77], v[76:77], v[224:225]
	v_pk_mul_f32 v[78:79], v[78:79], v[224:225]
	v_pk_mul_f32 v[68:69], v[68:69], v[224:225]
	v_pk_mul_f32 v[70:71], v[70:71], v[224:225]
	v_pk_mul_f32 v[72:73], v[72:73], v[224:225]
	v_pk_mul_f32 v[74:75], v[74:75], v[224:225]
	v_pk_mul_f32 v[64:65], v[64:65], v[224:225]
	v_pk_mul_f32 v[66:67], v[66:67], v[224:225]
	v_exp_f32_e32 v76, v76
	v_exp_f32_e32 v77, v77
	v_exp_f32_e32 v78, v78
	v_exp_f32_e32 v79, v79
	v_exp_f32_e32 v68, v68
	v_exp_f32_e32 v69, v69
	v_exp_f32_e32 v70, v70
	v_exp_f32_e32 v71, v71
	v_exp_f32_e32 v72, v72
	v_exp_f32_e32 v73, v73
	v_exp_f32_e32 v74, v74
	v_exp_f32_e32 v75, v75
	v_exp_f32_e32 v64, v64
	v_exp_f32_e32 v65, v65
	v_exp_f32_e32 v66, v66
	v_exp_f32_e32 v67, v67
	v_pk_add_f32 v[76:77], v[76:77], 1.0 op_sel_hi:[1,0]
	v_pk_add_f32 v[78:79], v[78:79], 1.0 op_sel_hi:[1,0]
	v_pk_add_f32 v[68:69], v[68:69], 1.0 op_sel_hi:[1,0]
	v_pk_add_f32 v[70:71], v[70:71], 1.0 op_sel_hi:[1,0]
	v_pk_add_f32 v[72:73], v[72:73], 1.0 op_sel_hi:[1,0]
	v_pk_add_f32 v[74:75], v[74:75], 1.0 op_sel_hi:[1,0]
	v_pk_add_f32 v[64:65], v[64:65], 1.0 op_sel_hi:[1,0]
	v_pk_add_f32 v[66:67], v[66:67], 1.0 op_sel_hi:[1,0]
	v_rcp_f32_e32 v76, v76
	v_rcp_f32_e32 v77, v77
	v_rcp_f32_e32 v78, v78
	v_rcp_f32_e32 v79, v79
	v_rcp_f32_e32 v68, v68
	v_rcp_f32_e32 v69, v69
	v_rcp_f32_e32 v70, v70
	v_rcp_f32_e32 v71, v71
	v_rcp_f32_e32 v72, v72
	v_rcp_f32_e32 v73, v73
	v_rcp_f32_e32 v74, v74
	v_rcp_f32_e32 v75, v75
	v_rcp_f32_e32 v64, v64
	v_rcp_f32_e32 v65, v65
	v_rcp_f32_e32 v66, v66
	v_rcp_f32_e32 v67, v67
	s_waitcnt vmcnt(11)
; __device__ __forceinline__ u32x4 pack8(const f32x4 a, const f32x4 b) { u32x4 w; w.x = pk2(a[0], a[1]); w.y = pk2(a[2], a[3]); w.z = pk2(b[0], b[1]); w.w = pk2(b[2], b[3]); return w; }
; __device__ __forceinline__ void unpack8(const u32x4 w, f32x4& a, f32x4& b) { a[0] = bflo(w.x); a[1] = bfhi(w.x); a[2] = bflo(w.y); a[3] = bfhi(w.y); b[0] = bflo(w.z); b[1] = bfhi(w.z); b[2] = bflo(w.w); b[3] = bfhi(w.w); }
;     __device__ __forceinline__ bool operator()(EPI_ARGS) const {
;     ...
;             for (int m = 0; m < 4; ++m) { const size_t off = ((size_t)u.pm * 256 + ROWLOC(ai, m)) * D + u.pn * 128 + 32 * wc + 8 * fq; ra[m] = *(const u32x4*)(yr + off); rc[m] = *(const u32x4*)(yc + off); }
; #pragma unroll
;             for (int m = 0; m < 4; ++m) {
;                 const size_t off = ((size_t)u.pm * 256 + ROWLOC(ai, m)) * D + u.pn * 128 + 32 * wc + 8 * fq;
;                 f32x4 a0, a1, c0, c1; unpack8(ra[m], a0, a1); unpack8(rc[m], c0, c1);
;                 const f32x4 o0 = vsig(acc[ai][0][m][0]) * a0 + vsig(acc[ai][1][m][0]) * c0, o1 = vsig(acc[ai][0][m][1]) * a1 + vsig(acc[ai][1][m][1]) * c1;
;                 *(u32x4*)(yr + off) = pack8(o0, o1);
;             }
	v_lshlrev_b32_e32 v162, 16, v168
	v_and_b32_e32 v163, 0xffff0000, v168
	v_lshlrev_b32_e32 v216, 16, v172
	v_and_b32_e32 v217, 0xffff0000, v172
	v_lshlrev_b32_e32 v178, 16, v169
	v_and_b32_e32 v179, 0xffff0000, v169
	v_lshlrev_b32_e32 v218, 16, v173
	v_and_b32_e32 v219, 0xffff0000, v173
	v_lshlrev_b32_e32 v212, 16, v170
	v_and_b32_e32 v213, 0xffff0000, v170
	v_lshlrev_b32_e32 v220, 16, v174
	v_and_b32_e32 v221, 0xffff0000, v174
	v_lshlrev_b32_e32 v214, 16, v171
	v_and_b32_e32 v215, 0xffff0000, v171
	v_lshlrev_b32_e32 v222, 16, v175
	v_and_b32_e32 v223, 0xffff0000, v175
	v_pk_mul_f32 v[216:217], v[72:73], v[216:217]
	v_pk_mul_f32 v[218:219], v[74:75], v[218:219]
	v_pk_fma_f32 v[162:163], v[76:77], v[162:163], v[216:217]
	v_pk_fma_f32 v[178:179], v[78:79], v[178:179], v[218:219]
	v_pk_mul_f32 v[220:221], v[64:65], v[220:221]
	v_pk_mul_f32 v[222:223], v[66:67], v[222:223]
	v_pk_fma_f32 v[212:213], v[68:69], v[212:213], v[220:221]
	v_pk_fma_f32 v[214:215], v[70:71], v[214:215], v[222:223]
	v_cvt_pk_bf16_f32 v168, v162, v163
	v_cvt_pk_bf16_f32 v169, v178, v179
	v_cvt_pk_bf16_f32 v170, v212, v213
	v_cvt_pk_bf16_f32 v171, v214, v215
	v_add_u32_e32 v177, 0x18000, v161
	global_store_dwordx4 v177, v[168:171], s[12:13]
	v_pk_mul_f32 v[60:61], v[60:61], v[224:225]
	v_pk_mul_f32 v[62:63], v[62:63], v[224:225]
	v_pk_mul_f32 v[52:53], v[52:53], v[224:225]
	v_pk_mul_f32 v[54:55], v[54:55], v[224:225]
	v_pk_mul_f32 v[56:57], v[56:57], v[224:225]
	v_pk_mul_f32 v[58:59], v[58:59], v[224:225]
	v_pk_mul_f32 v[48:49], v[48:49], v[224:225]
	v_pk_mul_f32 v[50:51], v[50:51], v[224:225]
	v_exp_f32_e32 v60, v60
	v_exp_f32_e32 v61, v61
	v_exp_f32_e32 v62, v62
	v_exp_f32_e32 v63, v63
	v_exp_f32_e32 v52, v52
	v_exp_f32_e32 v53, v53
	v_exp_f32_e32 v54, v54
	v_exp_f32_e32 v55, v55
	v_exp_f32_e32 v56, v56
	v_exp_f32_e32 v57, v57
	v_exp_f32_e32 v58, v58
	v_exp_f32_e32 v59, v59
	v_exp_f32_e32 v48, v48
	v_exp_f32_e32 v49, v49
	v_exp_f32_e32 v50, v50
	v_exp_f32_e32 v51, v51
	v_pk_add_f32 v[60:61], v[60:61], 1.0 op_sel_hi:[1,0]
	v_pk_add_f32 v[62:63], v[62:63], 1.0 op_sel_hi:[1,0]
	v_pk_add_f32 v[52:53], v[52:53], 1.0 op_sel_hi:[1,0]
	v_pk_add_f32 v[54:55], v[54:55], 1.0 op_sel_hi:[1,0]
	v_pk_add_f32 v[56:57], v[56:57], 1.0 op_sel_hi:[1,0]
	v_pk_add_f32 v[58:59], v[58:59], 1.0 op_sel_hi:[1,0]
	v_pk_add_f32 v[48:49], v[48:49], 1.0 op_sel_hi:[1,0]
	v_pk_add_f32 v[50:51], v[50:51], 1.0 op_sel_hi:[1,0]
	v_rcp_f32_e32 v60, v60
	v_rcp_f32_e32 v61, v61
	v_rcp_f32_e32 v62, v62
	v_rcp_f32_e32 v63, v63
	v_rcp_f32_e32 v52, v52
	v_rcp_f32_e32 v53, v53
	v_rcp_f32_e32 v54, v54
	v_rcp_f32_e32 v55, v55
	v_rcp_f32_e32 v56, v56
	v_rcp_f32_e32 v57, v57
	v_rcp_f32_e32 v58, v58
	v_rcp_f32_e32 v59, v59
	v_rcp_f32_e32 v48, v48
	v_rcp_f32_e32 v49, v49
	v_rcp_f32_e32 v50, v50
	v_rcp_f32_e32 v51, v51
	s_waitcnt vmcnt(10)
	v_lshlrev_b32_e32 v162, 16, v180
	v_and_b32_e32 v163, 0xffff0000, v180
	v_lshlrev_b32_e32 v216, 16, v184
	v_and_b32_e32 v217, 0xffff0000, v184
	v_lshlrev_b32_e32 v178, 16, v181
	v_and_b32_e32 v179, 0xffff0000, v181
	v_lshlrev_b32_e32 v218, 16, v185
	v_and_b32_e32 v219, 0xffff0000, v185
	v_lshlrev_b32_e32 v212, 16, v182
	v_and_b32_e32 v213, 0xffff0000, v182
	v_lshlrev_b32_e32 v220, 16, v186
	v_and_b32_e32 v221, 0xffff0000, v186
	v_lshlrev_b32_e32 v214, 16, v183
	v_and_b32_e32 v215, 0xffff0000, v183
	v_lshlrev_b32_e32 v222, 16, v187
	v_and_b32_e32 v223, 0xffff0000, v187
	v_pk_mul_f32 v[216:217], v[56:57], v[216:217]
	v_pk_mul_f32 v[218:219], v[58:59], v[218:219]
	v_pk_fma_f32 v[162:163], v[60:61], v[162:163], v[216:217]
	v_pk_fma_f32 v[178:179], v[62:63], v[178:179], v[218:219]
	v_pk_mul_f32 v[220:221], v[48:49], v[220:221]
	v_pk_mul_f32 v[222:223], v[50:51], v[222:223]
	v_pk_fma_f32 v[212:213], v[52:53], v[212:213], v[220:221]
	v_pk_fma_f32 v[214:215], v[54:55], v[214:215], v[222:223]
	v_cvt_pk_bf16_f32 v180, v162, v163
	v_cvt_pk_bf16_f32 v181, v178, v179
	v_cvt_pk_bf16_f32 v182, v212, v213
	v_cvt_pk_bf16_f32 v183, v214, v215
	v_add_u32_e32 v177, 0x40000, v161
	global_store_dwordx4 v177, v[180:183], s[12:13]
	v_pk_mul_f32 v[44:45], v[44:45], v[224:225]
	v_pk_mul_f32 v[46:47], v[46:47], v[224:225]
	v_pk_mul_f32 v[36:37], v[36:37], v[224:225]
	v_pk_mul_f32 v[38:39], v[38:39], v[224:225]
	v_pk_mul_f32 v[40:41], v[40:41], v[224:225]
	v_pk_mul_f32 v[42:43], v[42:43], v[224:225]
	v_pk_mul_f32 v[32:33], v[32:33], v[224:225]
	v_pk_mul_f32 v[34:35], v[34:35], v[224:225]
	v_exp_f32_e32 v44, v44
	v_exp_f32_e32 v45, v45
	v_exp_f32_e32 v46, v46
	v_exp_f32_e32 v47, v47
	v_exp_f32_e32 v36, v36
	v_exp_f32_e32 v37, v37
	v_exp_f32_e32 v38, v38
	v_exp_f32_e32 v39, v39
	v_exp_f32_e32 v40, v40
	v_exp_f32_e32 v41, v41
	v_exp_f32_e32 v42, v42
	v_exp_f32_e32 v43, v43
	v_exp_f32_e32 v32, v32
	v_exp_f32_e32 v33, v33
	v_exp_f32_e32 v34, v34
	v_exp_f32_e32 v35, v35
	v_pk_add_f32 v[44:45], v[44:45], 1.0 op_sel_hi:[1,0]
	v_pk_add_f32 v[46:47], v[46:47], 1.0 op_sel_hi:[1,0]
	v_pk_add_f32 v[36:37], v[36:37], 1.0 op_sel_hi:[1,0]
	v_pk_add_f32 v[38:39], v[38:39], 1.0 op_sel_hi:[1,0]
	v_pk_add_f32 v[40:41], v[40:41], 1.0 op_sel_hi:[1,0]
	v_pk_add_f32 v[42:43], v[42:43], 1.0 op_sel_hi:[1,0]
	v_pk_add_f32 v[32:33], v[32:33], 1.0 op_sel_hi:[1,0]
	v_pk_add_f32 v[34:35], v[34:35], 1.0 op_sel_hi:[1,0]
	v_rcp_f32_e32 v44, v44
	v_rcp_f32_e32 v45, v45
	v_rcp_f32_e32 v46, v46
	v_rcp_f32_e32 v47, v47
	v_rcp_f32_e32 v36, v36
	v_rcp_f32_e32 v37, v37
	v_rcp_f32_e32 v38, v38
	v_rcp_f32_e32 v39, v39
	v_rcp_f32_e32 v40, v40
	v_rcp_f32_e32 v41, v41
	v_rcp_f32_e32 v42, v42
	v_rcp_f32_e32 v43, v43
	v_rcp_f32_e32 v32, v32
	v_rcp_f32_e32 v33, v33
	v_rcp_f32_e32 v34, v34
	v_rcp_f32_e32 v35, v35
	s_waitcnt vmcnt(9)
; __device__ __forceinline__ u32x4 pack8(const f32x4 a, const f32x4 b) { u32x4 w; w.x = pk2(a[0], a[1]); w.y = pk2(a[2], a[3]); w.z = pk2(b[0], b[1]); w.w = pk2(b[2], b[3]); return w; }
; __device__ __forceinline__ void unpack8(const u32x4 w, f32x4& a, f32x4& b) { a[0] = bflo(w.x); a[1] = bfhi(w.x); a[2] = bflo(w.y); a[3] = bfhi(w.y); b[0] = bflo(w.z); b[1] = bfhi(w.z); b[2] = bflo(w.w); b[3] = bfhi(w.w); }
;     __device__ __forceinline__ bool operator()(EPI_ARGS) const {
;     ...
;             for (int m = 0; m < 4; ++m) { const size_t off = ((size_t)u.pm * 256 + ROWLOC(ai, m)) * D + u.pn * 128 + 32 * wc + 8 * fq; ra[m] = *(const u32x4*)(yr + off); rc[m] = *(const u32x4*)(yc + off); }
; #pragma unroll
;             for (int m = 0; m < 4; ++m) {
;                 const size_t off = ((size_t)u.pm * 256 + ROWLOC(ai, m)) * D + u.pn * 128 + 32 * wc + 8 * fq;
;                 f32x4 a0, a1, c0, c1; unpack8(ra[m], a0, a1); unpack8(rc[m], c0, c1);
;                 const f32x4 o0 = vsig(acc[ai][0][m][0]) * a0 + vsig(acc[ai][1][m][0]) * c0, o1 = vsig(acc[ai][0][m][1]) * a1 + vsig(acc[ai][1][m][1]) * c1;
;                 *(u32x4*)(yr + off) = pack8(o0, o1);
;             }
;             asm volatile("" ::: "memory");
;         }
	v_lshlrev_b32_e32 v162, 16, v188
	v_and_b32_e32 v163, 0xffff0000, v188
	v_lshlrev_b32_e32 v216, 16, v192
	v_and_b32_e32 v217, 0xffff0000, v192
	v_lshlrev_b32_e32 v178, 16, v189
	v_and_b32_e32 v179, 0xffff0000, v189
	v_lshlrev_b32_e32 v218, 16, v193
	v_and_b32_e32 v219, 0xffff0000, v193
	v_lshlrev_b32_e32 v212, 16, v190
	v_and_b32_e32 v213, 0xffff0000, v190
	v_lshlrev_b32_e32 v220, 16, v194
	v_and_b32_e32 v221, 0xffff0000, v194
	v_lshlrev_b32_e32 v214, 16, v191
	v_and_b32_e32 v215, 0xffff0000, v191
	v_lshlrev_b32_e32 v222, 16, v195
	v_and_b32_e32 v223, 0xffff0000, v195
	v_pk_mul_f32 v[216:217], v[40:41], v[216:217]
	v_pk_mul_f32 v[218:219], v[42:43], v[218:219]
	v_pk_fma_f32 v[162:163], v[44:45], v[162:163], v[216:217]
	v_pk_fma_f32 v[178:179], v[46:47], v[178:179], v[218:219]
	v_pk_mul_f32 v[220:221], v[32:33], v[220:221]
	v_pk_mul_f32 v[222:223], v[34:35], v[222:223]
	v_pk_fma_f32 v[212:213], v[36:37], v[212:213], v[220:221]
	v_pk_fma_f32 v[214:215], v[38:39], v[214:215], v[222:223]
	v_cvt_pk_bf16_f32 v188, v162, v163
	v_cvt_pk_bf16_f32 v189, v178, v179
	v_cvt_pk_bf16_f32 v190, v212, v213
	v_cvt_pk_bf16_f32 v191, v214, v215
	v_add_u32_e32 v177, 0x48000, v161
	global_store_dwordx4 v177, v[188:191], s[12:13]
	v_pk_mul_f32 v[28:29], v[28:29], v[224:225]
	v_pk_mul_f32 v[30:31], v[30:31], v[224:225]
	v_pk_mul_f32 v[20:21], v[20:21], v[224:225]
	v_pk_mul_f32 v[22:23], v[22:23], v[224:225]
	v_pk_mul_f32 v[24:25], v[24:25], v[224:225]
	v_pk_mul_f32 v[26:27], v[26:27], v[224:225]
	v_pk_mul_f32 v[16:17], v[16:17], v[224:225]
	v_pk_mul_f32 v[18:19], v[18:19], v[224:225]
	v_exp_f32_e32 v28, v28
	v_exp_f32_e32 v29, v29
	v_exp_f32_e32 v30, v30
	v_exp_f32_e32 v31, v31
	v_exp_f32_e32 v20, v20
	v_exp_f32_e32 v21, v21
	v_exp_f32_e32 v22, v22
	v_exp_f32_e32 v23, v23
	v_exp_f32_e32 v24, v24
	v_exp_f32_e32 v25, v25
	v_exp_f32_e32 v26, v26
	v_exp_f32_e32 v27, v27
	v_exp_f32_e32 v16, v16
	v_exp_f32_e32 v17, v17
	v_exp_f32_e32 v18, v18
	v_exp_f32_e32 v19, v19
	v_pk_add_f32 v[28:29], v[28:29], 1.0 op_sel_hi:[1,0]
	v_pk_add_f32 v[30:31], v[30:31], 1.0 op_sel_hi:[1,0]
	v_pk_add_f32 v[20:21], v[20:21], 1.0 op_sel_hi:[1,0]
	v_pk_add_f32 v[22:23], v[22:23], 1.0 op_sel_hi:[1,0]
	v_pk_add_f32 v[24:25], v[24:25], 1.0 op_sel_hi:[1,0]
	v_pk_add_f32 v[26:27], v[26:27], 1.0 op_sel_hi:[1,0]
	v_pk_add_f32 v[16:17], v[16:17], 1.0 op_sel_hi:[1,0]
	v_pk_add_f32 v[18:19], v[18:19], 1.0 op_sel_hi:[1,0]
	v_rcp_f32_e32 v28, v28
	v_rcp_f32_e32 v29, v29
	v_rcp_f32_e32 v30, v30
	v_rcp_f32_e32 v31, v31
	v_rcp_f32_e32 v20, v20
	v_rcp_f32_e32 v21, v21
	v_rcp_f32_e32 v22, v22
	v_rcp_f32_e32 v23, v23
	v_rcp_f32_e32 v24, v24
	v_rcp_f32_e32 v25, v25
	v_rcp_f32_e32 v26, v26
	v_rcp_f32_e32 v27, v27
	v_rcp_f32_e32 v16, v16
	v_rcp_f32_e32 v17, v17
	v_rcp_f32_e32 v18, v18
	v_rcp_f32_e32 v19, v19
	s_waitcnt vmcnt(8)
	v_lshlrev_b32_e32 v162, 16, v196
	v_and_b32_e32 v163, 0xffff0000, v196
	v_lshlrev_b32_e32 v216, 16, v200
	v_and_b32_e32 v217, 0xffff0000, v200
	v_lshlrev_b32_e32 v178, 16, v197
	v_and_b32_e32 v179, 0xffff0000, v197
	v_lshlrev_b32_e32 v218, 16, v201
	v_and_b32_e32 v219, 0xffff0000, v201
	v_lshlrev_b32_e32 v212, 16, v198
	v_and_b32_e32 v213, 0xffff0000, v198
	v_lshlrev_b32_e32 v220, 16, v202
	v_and_b32_e32 v221, 0xffff0000, v202
	v_lshlrev_b32_e32 v214, 16, v199
	v_and_b32_e32 v215, 0xffff0000, v199
	v_lshlrev_b32_e32 v222, 16, v203
	v_and_b32_e32 v223, 0xffff0000, v203
	v_pk_mul_f32 v[216:217], v[24:25], v[216:217]
	v_pk_mul_f32 v[218:219], v[26:27], v[218:219]
	v_pk_fma_f32 v[162:163], v[28:29], v[162:163], v[216:217]
	v_pk_fma_f32 v[178:179], v[30:31], v[178:179], v[218:219]
	v_pk_mul_f32 v[220:221], v[16:17], v[220:221]
	v_pk_mul_f32 v[222:223], v[18:19], v[222:223]
	v_pk_fma_f32 v[212:213], v[20:21], v[212:213], v[220:221]
	v_pk_fma_f32 v[214:215], v[22:23], v[214:215], v[222:223]
	v_cvt_pk_bf16_f32 v196, v162, v163
	v_cvt_pk_bf16_f32 v197, v178, v179
	v_cvt_pk_bf16_f32 v198, v212, v213
	v_cvt_pk_bf16_f32 v199, v214, v215
	v_add_u32_e32 v177, 0x50000, v161
	global_store_dwordx4 v177, v[196:199], s[12:13]
	v_pk_mul_f32 v[12:13], v[12:13], v[224:225]
	v_pk_mul_f32 v[14:15], v[14:15], v[224:225]
	v_pk_mul_f32 v[4:5], v[4:5], v[224:225]
	v_pk_mul_f32 v[6:7], v[6:7], v[224:225]
	v_pk_mul_f32 v[8:9], v[8:9], v[224:225]
	v_pk_mul_f32 v[10:11], v[10:11], v[224:225]
	v_pk_mul_f32 v[0:1], v[0:1], v[224:225]
	v_pk_mul_f32 v[2:3], v[2:3], v[224:225]
	v_exp_f32_e32 v12, v12
	v_exp_f32_e32 v13, v13
	v_exp_f32_e32 v14, v14
	v_exp_f32_e32 v15, v15
	v_exp_f32_e32 v4, v4
	v_exp_f32_e32 v5, v5
	v_exp_f32_e32 v6, v6
	v_exp_f32_e32 v7, v7
	v_exp_f32_e32 v8, v8
	v_exp_f32_e32 v9, v9
	v_exp_f32_e32 v10, v10
	v_exp_f32_e32 v11, v11
	v_exp_f32_e32 v0, v0
	v_exp_f32_e32 v1, v1
	v_exp_f32_e32 v2, v2
	v_exp_f32_e32 v3, v3
	v_pk_add_f32 v[12:13], v[12:13], 1.0 op_sel_hi:[1,0]
	v_pk_add_f32 v[14:15], v[14:15], 1.0 op_sel_hi:[1,0]
	v_pk_add_f32 v[4:5], v[4:5], 1.0 op_sel_hi:[1,0]
	v_pk_add_f32 v[6:7], v[6:7], 1.0 op_sel_hi:[1,0]
	v_pk_add_f32 v[8:9], v[8:9], 1.0 op_sel_hi:[1,0]
	v_pk_add_f32 v[10:11], v[10:11], 1.0 op_sel_hi:[1,0]
	v_pk_add_f32 v[0:1], v[0:1], 1.0 op_sel_hi:[1,0]
	v_pk_add_f32 v[2:3], v[2:3], 1.0 op_sel_hi:[1,0]
	v_rcp_f32_e32 v12, v12
	v_rcp_f32_e32 v13, v13
	v_rcp_f32_e32 v14, v14
	v_rcp_f32_e32 v15, v15
	v_rcp_f32_e32 v4, v4
	v_rcp_f32_e32 v5, v5
	v_rcp_f32_e32 v6, v6
	v_rcp_f32_e32 v7, v7
	v_rcp_f32_e32 v8, v8
	v_rcp_f32_e32 v9, v9
	v_rcp_f32_e32 v10, v10
	v_rcp_f32_e32 v11, v11
	v_rcp_f32_e32 v0, v0
	v_rcp_f32_e32 v1, v1
	v_rcp_f32_e32 v2, v2
	v_rcp_f32_e32 v3, v3
	s_waitcnt vmcnt(7)
	v_lshlrev_b32_e32 v162, 16, v204
	v_and_b32_e32 v163, 0xffff0000, v204
	v_lshlrev_b32_e32 v216, 16, v208
	v_and_b32_e32 v217, 0xffff0000, v208
	v_lshlrev_b32_e32 v178, 16, v205
	v_and_b32_e32 v179, 0xffff0000, v205
	v_lshlrev_b32_e32 v218, 16, v209
	v_and_b32_e32 v219, 0xffff0000, v209
	v_lshlrev_b32_e32 v212, 16, v206
	v_and_b32_e32 v213, 0xffff0000, v206
	v_lshlrev_b32_e32 v220, 16, v210
	v_and_b32_e32 v221, 0xffff0000, v210
	v_lshlrev_b32_e32 v214, 16, v207
	v_and_b32_e32 v215, 0xffff0000, v207
	v_lshlrev_b32_e32 v222, 16, v211
	v_and_b32_e32 v223, 0xffff0000, v211
	v_pk_mul_f32 v[216:217], v[8:9], v[216:217]
	v_pk_mul_f32 v[218:219], v[10:11], v[218:219]
	v_pk_fma_f32 v[162:163], v[12:13], v[162:163], v[216:217]
	v_pk_fma_f32 v[178:179], v[14:15], v[178:179], v[218:219]
	v_pk_mul_f32 v[220:221], v[0:1], v[220:221]
	v_pk_mul_f32 v[222:223], v[2:3], v[222:223]
	v_pk_fma_f32 v[212:213], v[4:5], v[212:213], v[220:221]
	v_pk_fma_f32 v[214:215], v[6:7], v[214:215], v[222:223]
	v_cvt_pk_bf16_f32 v204, v162, v163
	v_cvt_pk_bf16_f32 v205, v178, v179
	v_cvt_pk_bf16_f32 v206, v212, v213
	v_cvt_pk_bf16_f32 v207, v214, v215
	v_add_u32_e32 v177, 0x58000, v161
	global_store_dwordx4 v177, v[204:207], s[12:13]
	s_andn2_b64 vcc, exec, s[8:9]
	s_mov_b64 s[8:9], -1
	s_cbranch_vccnz .LBB0_1266
	s_andn2_b64 vcc, exec, s[10:11]
	s_cbranch_vccnz .LBB0_1265
	s_barrier
	s_branch .LBB0_1265

; __device__ __forceinline__ u32x4 pack8(const f32x4 a, const f32x4 b) { u32x4 w; w.x = pk2(a[0], a[1]); w.y = pk2(a[2], a[3]); w.z = pk2(b[0], b[1]); w.w = pk2(b[2], b[3]); return w; }
; __device__ __forceinline__ void unpack8(const u32x4 w, f32x4& a, f32x4& b) { a[0] = bflo(w.x); a[1] = bfhi(w.x); a[2] = bflo(w.y); a[3] = bfhi(w.y); b[0] = bflo(w.z); b[1] = bfhi(w.z); b[2] = bflo(w.w); b[3] = bfhi(w.w); }
;     __device__ __forceinline__ bool operator()(EPI_ARGS) const {
;         const int ms = u.pm < 64 ? 0 : (u.pm < 128 ? 1 : 2);
;         const float* g = mods + ms * (NMOD * D) + gidx * D;
; #pragma unroll
;         for (int bj = 0; bj < 2; ++bj) {
;             const int col = u.pn * 256 + COLLOC(bj);
;             const f32x4 g0 = *(const f32x4*)(g + col) * coef, g1 = *(const f32x4*)(g + col + 4) * coef;
;             if (u.kind == 1) {
;                 float* dst = dst_ctx + (size_t)(u.pm - 128) * 256 * D;
; #pragma unroll
;                 for (int ai = 0; ai < 2; ++ai)
; #pragma unroll
;                     for (int m = 0; m < 4; ++m) {
;                         float* sl = dst + (size_t)u.w * (TC * D) + (size_t)ROWLOC(ai, m) * D + col;
;                         *(f32x4*)sl = g0 * acc[ai][bj][m][0]; *(f32x4*)(sl + 4) = g1 * acc[ai][bj][m][1];
;                     }
;             } else {
;                 bf16_t* hp = hbuf + (size_t)u.pm * 256 * D;
; #pragma unroll
;                 for (int ai = 0; ai < 2; ++ai) {
;                     f32x4 r0[4], r1[4];
; #pragma unroll
;                     for (int m = 0; m < 4; ++m) { const size_t o = (size_t)ROWLOC(ai, m) * D + col;
;                         if (RES_BF16) unpack8(*(const u32x4*)(hp + o), r0[m], r1[m]);
;                         else { const float* rp = res_f32 + (size_t)u.pm * 256 * D + o; r0[m] = *(const f32x4*)rp; r1[m] = *(const f32x4*)(rp + 4); } }
; #pragma unroll
;                     for (int m = 0; m < 4; ++m) { const size_t o = (size_t)ROWLOC(ai, m) * D + col;
;                         *(u32x4*)(hp + o) = pack8(r0[m] + g0 * acc[ai][bj][m][0], r1[m] + g1 * acc[ai][bj][m][1]); }
;                 }
.LBB0_1361:
	s_cmpk_lt_i32 s16, 0x80
	s_cselect_b32 s17, s56, 0x4800
	s_cmp_gt_i32 s16, 63
	s_cselect_b32 s17, s17, 0
	s_lshl_b32 s17, s17, 2
	s_add_u32 s17, s6, s17
	s_addc_u32 s23, s7, 0
	s_add_u32 s22, s17, 0x3d05000
	s_addc_u32 s23, s23, 0
	s_lshl_b32 s17, s58, 8
	s_or_b32 s17, s17, s47
	s_lshl_b32 s24, s16, 19
	v_lshl_add_u32 v230, v173, 3, s17
	s_add_u32 s24, s44, s24
	v_add_u32_e32 v231, s46, v172
	s_addc_u32 s25, s45, 0
	v_lshlrev_b32_e32 v233, 2, v230
	v_lshlrev_b32_e32 v230, 1, v230
	v_lshl_add_u32 v232, v231, 11, v230
	global_load_dwordx4 v[208:211], v233, s[22:23]
	global_load_dwordx4 v[212:215], v233, s[22:23] offset:16
	global_load_dwordx4 v[216:219], v233, s[22:23] offset:512
	global_load_dwordx4 v[220:223], v233, s[22:23] offset:528
	global_load_dwordx4 v[128:131], v232, s[24:25]
	global_load_dwordx4 v[132:135], v232, s[24:25] offset:256
	v_add_u32_e32 v234, 0x8000, v232
	global_load_dwordx4 v[136:139], v234, s[24:25]
	global_load_dwordx4 v[144:147], v234, s[24:25] offset:256
	v_add_u32_e32 v234, 0x10000, v232
	global_load_dwordx4 v[148:151], v234, s[24:25]
	global_load_dwordx4 v[152:155], v234, s[24:25] offset:256
	v_add_u32_e32 v234, 0x18000, v232
	global_load_dwordx4 v[156:159], v234, s[24:25]
	global_load_dwordx4 v[160:163], v234, s[24:25] offset:256
	v_add_u32_e32 v234, 0x40000, v232
	global_load_dwordx4 v[164:167], v234, s[24:25]
	global_load_dwordx4 v[180:183], v234, s[24:25] offset:256
	v_add_u32_e32 v234, 0x48000, v232
	global_load_dwordx4 v[184:187], v234, s[24:25]
	global_load_dwordx4 v[188:191], v234, s[24:25] offset:256
	v_add_u32_e32 v234, 0x50000, v232
	global_load_dwordx4 v[192:195], v234, s[24:25]
	global_load_dwordx4 v[196:199], v234, s[24:25] offset:256
	v_add_u32_e32 v234, 0x58000, v232
	global_load_dwordx4 v[200:203], v234, s[24:25]
	global_load_dwordx4 v[204:207], v234, s[24:25] offset:256
	s_waitcnt vmcnt(15)
	v_lshlrev_b32_e32 v168, 16, v128
	v_and_b32_e32 v169, 0xffff0000, v128
	v_lshlrev_b32_e32 v224, 16, v129
	v_and_b32_e32 v225, 0xffff0000, v129
	v_lshlrev_b32_e32 v226, 16, v130
	v_and_b32_e32 v227, 0xffff0000, v130
	v_lshlrev_b32_e32 v228, 16, v131
	v_and_b32_e32 v229, 0xffff0000, v131
	v_pk_fma_f32 v[168:169], v[84:85], v[208:209], v[168:169]
	v_pk_fma_f32 v[224:225], v[86:87], v[210:211], v[224:225]
	v_pk_fma_f32 v[226:227], v[76:77], v[212:213], v[226:227]
	v_pk_fma_f32 v[228:229], v[78:79], v[214:215], v[228:229]
	v_cvt_pk_bf16_f32 v128, v168, v169
	v_cvt_pk_bf16_f32 v129, v224, v225
	v_cvt_pk_bf16_f32 v130, v226, v227
	v_cvt_pk_bf16_f32 v131, v228, v229
	global_store_dwordx4 v232, v[128:131], s[24:25]
	s_waitcnt vmcnt(15)
	v_lshlrev_b32_e32 v168, 16, v132
	v_and_b32_e32 v169, 0xffff0000, v132
	v_lshlrev_b32_e32 v224, 16, v133
	v_and_b32_e32 v225, 0xffff0000, v133
	v_lshlrev_b32_e32 v226, 16, v134
	v_and_b32_e32 v227, 0xffff0000, v134
	v_lshlrev_b32_e32 v228, 16, v135
	v_and_b32_e32 v229, 0xffff0000, v135
	v_pk_fma_f32 v[168:169], v[60:61], v[216:217], v[168:169]
	v_pk_fma_f32 v[224:225], v[62:63], v[218:219], v[224:225]
	v_pk_fma_f32 v[226:227], v[56:57], v[220:221], v[226:227]
	v_pk_fma_f32 v[228:229], v[58:59], v[222:223], v[228:229]
	v_cvt_pk_bf16_f32 v132, v168, v169
	v_cvt_pk_bf16_f32 v133, v224, v225
	v_cvt_pk_bf16_f32 v134, v226, v227
	v_cvt_pk_bf16_f32 v135, v228, v229
	global_store_dwordx4 v232, v[132:135], s[24:25] offset:256
	s_waitcnt vmcnt(15)
	v_lshlrev_b32_e32 v168, 16, v136
	v_and_b32_e32 v169, 0xffff0000, v136
	v_lshlrev_b32_e32 v224, 16, v137
	v_and_b32_e32 v225, 0xffff0000, v137
	v_lshlrev_b32_e32 v226, 16, v138
	v_and_b32_e32 v227, 0xffff0000, v138
	v_lshlrev_b32_e32 v228, 16, v139
	v_and_b32_e32 v229, 0xffff0000, v139
	v_pk_fma_f32 v[168:169], v[124:125], v[208:209], v[168:169]
	v_pk_fma_f32 v[224:225], v[126:127], v[210:211], v[224:225]
	v_pk_fma_f32 v[226:227], v[120:121], v[212:213], v[226:227]
	v_pk_fma_f32 v[228:229], v[122:123], v[214:215], v[228:229]
	v_cvt_pk_bf16_f32 v136, v168, v169
	v_cvt_pk_bf16_f32 v137, v224, v225
	v_cvt_pk_bf16_f32 v138, v226, v227
	v_cvt_pk_bf16_f32 v139, v228, v229
	v_add_u32_e32 v234, 0x8000, v232
	global_store_dwordx4 v234, v[136:139], s[24:25]
	s_waitcnt vmcnt(15)
	v_lshlrev_b32_e32 v168, 16, v144
	v_and_b32_e32 v169, 0xffff0000, v144
	v_lshlrev_b32_e32 v224, 16, v145
	v_and_b32_e32 v225, 0xffff0000, v145
	v_lshlrev_b32_e32 v226, 16, v146
	v_and_b32_e32 v227, 0xffff0000, v146
	v_lshlrev_b32_e32 v228, 16, v147
	v_and_b32_e32 v229, 0xffff0000, v147
	v_pk_fma_f32 v[168:169], v[52:53], v[216:217], v[168:169]
	v_pk_fma_f32 v[224:225], v[54:55], v[218:219], v[224:225]
	v_pk_fma_f32 v[226:227], v[48:49], v[220:221], v[226:227]
	v_pk_fma_f32 v[228:229], v[50:51], v[222:223], v[228:229]
	v_cvt_pk_bf16_f32 v144, v168, v169
	v_cvt_pk_bf16_f32 v145, v224, v225
	v_cvt_pk_bf16_f32 v146, v226, v227
	v_cvt_pk_bf16_f32 v147, v228, v229
	v_add_u32_e32 v234, 0x8000, v232
	global_store_dwordx4 v234, v[144:147], s[24:25] offset:256
	s_waitcnt vmcnt(15)
	v_lshlrev_b32_e32 v168, 16, v148
	v_and_b32_e32 v169, 0xffff0000, v148
	v_lshlrev_b32_e32 v224, 16, v149
	v_and_b32_e32 v225, 0xffff0000, v149
	v_lshlrev_b32_e32 v226, 16, v150
	v_and_b32_e32 v227, 0xffff0000, v150
	v_lshlrev_b32_e32 v228, 16, v151
	v_and_b32_e32 v229, 0xffff0000, v151
	v_pk_fma_f32 v[168:169], v[116:117], v[208:209], v[168:169]
	v_pk_fma_f32 v[224:225], v[118:119], v[210:211], v[224:225]
	v_pk_fma_f32 v[226:227], v[112:113], v[212:213], v[226:227]
	v_pk_fma_f32 v[228:229], v[114:115], v[214:215], v[228:229]
	v_cvt_pk_bf16_f32 v148, v168, v169
	v_cvt_pk_bf16_f32 v149, v224, v225
	v_cvt_pk_bf16_f32 v150, v226, v227
	v_cvt_pk_bf16_f32 v151, v228, v229
	v_add_u32_e32 v234, 0x10000, v232
	global_store_dwordx4 v234, v[148:151], s[24:25]
	s_waitcnt vmcnt(15)
; __device__ __forceinline__ u32x4 pack8(const f32x4 a, const f32x4 b) { u32x4 w; w.x = pk2(a[0], a[1]); w.y = pk2(a[2], a[3]); w.z = pk2(b[0], b[1]); w.w = pk2(b[2], b[3]); return w; }
; __device__ __forceinline__ void unpack8(const u32x4 w, f32x4& a, f32x4& b) { a[0] = bflo(w.x); a[1] = bfhi(w.x); a[2] = bflo(w.y); a[3] = bfhi(w.y); b[0] = bflo(w.z); b[1] = bfhi(w.z); b[2] = bflo(w.w); b[3] = bfhi(w.w); }
;     __device__ __forceinline__ bool operator()(EPI_ARGS) const {
;     ...
;                 bf16_t* hp = hbuf + (size_t)u.pm * 256 * D;
; #pragma unroll
;                 for (int ai = 0; ai < 2; ++ai) {
;                     f32x4 r0[4], r1[4];
; #pragma unroll
;                     for (int m = 0; m < 4; ++m) { const size_t o = (size_t)ROWLOC(ai, m) * D + col;
;                         if (RES_BF16) unpack8(*(const u32x4*)(hp + o), r0[m], r1[m]);
;                         else { const float* rp = res_f32 + (size_t)u.pm * 256 * D + o; r0[m] = *(const f32x4*)rp; r1[m] = *(const f32x4*)(rp + 4); } }
; #pragma unroll
;                     for (int m = 0; m < 4; ++m) { const size_t o = (size_t)ROWLOC(ai, m) * D + col;
;                         *(u32x4*)(hp + o) = pack8(r0[m] + g0 * acc[ai][bj][m][0], r1[m] + g1 * acc[ai][bj][m][1]); }
	v_lshlrev_b32_e32 v168, 16, v152
	v_and_b32_e32 v169, 0xffff0000, v152
	v_lshlrev_b32_e32 v224, 16, v153
	v_and_b32_e32 v225, 0xffff0000, v153
	v_lshlrev_b32_e32 v226, 16, v154
	v_and_b32_e32 v227, 0xffff0000, v154
	v_lshlrev_b32_e32 v228, 16, v155
	v_and_b32_e32 v229, 0xffff0000, v155
	v_pk_fma_f32 v[168:169], v[44:45], v[216:217], v[168:169]
	v_pk_fma_f32 v[224:225], v[46:47], v[218:219], v[224:225]
	v_pk_fma_f32 v[226:227], v[40:41], v[220:221], v[226:227]
	v_pk_fma_f32 v[228:229], v[42:43], v[222:223], v[228:229]
	v_cvt_pk_bf16_f32 v152, v168, v169
	v_cvt_pk_bf16_f32 v153, v224, v225
	v_cvt_pk_bf16_f32 v154, v226, v227
	v_cvt_pk_bf16_f32 v155, v228, v229
	v_add_u32_e32 v234, 0x10000, v232
	global_store_dwordx4 v234, v[152:155], s[24:25] offset:256
	s_waitcnt vmcnt(15)
	v_lshlrev_b32_e32 v168, 16, v156
	v_and_b32_e32 v169, 0xffff0000, v156
	v_lshlrev_b32_e32 v224, 16, v157
	v_and_b32_e32 v225, 0xffff0000, v157
	v_lshlrev_b32_e32 v226, 16, v158
	v_and_b32_e32 v227, 0xffff0000, v158
	v_lshlrev_b32_e32 v228, 16, v159
	v_and_b32_e32 v229, 0xffff0000, v159
	v_pk_fma_f32 v[168:169], v[108:109], v[208:209], v[168:169]
	v_pk_fma_f32 v[224:225], v[110:111], v[210:211], v[224:225]
	v_pk_fma_f32 v[226:227], v[104:105], v[212:213], v[226:227]
	v_pk_fma_f32 v[228:229], v[106:107], v[214:215], v[228:229]
	v_cvt_pk_bf16_f32 v156, v168, v169
	v_cvt_pk_bf16_f32 v157, v224, v225
	v_cvt_pk_bf16_f32 v158, v226, v227
	v_cvt_pk_bf16_f32 v159, v228, v229
	v_add_u32_e32 v234, 0x18000, v232
	global_store_dwordx4 v234, v[156:159], s[24:25]
	s_waitcnt vmcnt(15)
	v_lshlrev_b32_e32 v168, 16, v160
	v_and_b32_e32 v169, 0xffff0000, v160
	v_lshlrev_b32_e32 v224, 16, v161
	v_and_b32_e32 v225, 0xffff0000, v161
	v_lshlrev_b32_e32 v226, 16, v162
	v_and_b32_e32 v227, 0xffff0000, v162
	v_lshlrev_b32_e32 v228, 16, v163
	v_and_b32_e32 v229, 0xffff0000, v163
	v_pk_fma_f32 v[168:169], v[36:37], v[216:217], v[168:169]
	v_pk_fma_f32 v[224:225], v[38:39], v[218:219], v[224:225]
	v_pk_fma_f32 v[226:227], v[32:33], v[220:221], v[226:227]
	v_pk_fma_f32 v[228:229], v[34:35], v[222:223], v[228:229]
	v_cvt_pk_bf16_f32 v160, v168, v169
	v_cvt_pk_bf16_f32 v161, v224, v225
	v_cvt_pk_bf16_f32 v162, v226, v227
	v_cvt_pk_bf16_f32 v163, v228, v229
	v_add_u32_e32 v234, 0x18000, v232
	global_store_dwordx4 v234, v[160:163], s[24:25] offset:256
	s_waitcnt vmcnt(15)
	v_lshlrev_b32_e32 v168, 16, v164
	v_and_b32_e32 v169, 0xffff0000, v164
	v_lshlrev_b32_e32 v224, 16, v165
	v_and_b32_e32 v225, 0xffff0000, v165
	v_lshlrev_b32_e32 v226, 16, v166
	v_and_b32_e32 v227, 0xffff0000, v166
	v_lshlrev_b32_e32 v228, 16, v167
	v_and_b32_e32 v229, 0xffff0000, v167
	v_pk_fma_f32 v[168:169], v[100:101], v[208:209], v[168:169]
	v_pk_fma_f32 v[224:225], v[102:103], v[210:211], v[224:225]
	v_pk_fma_f32 v[226:227], v[96:97], v[212:213], v[226:227]
	v_pk_fma_f32 v[228:229], v[98:99], v[214:215], v[228:229]
	v_cvt_pk_bf16_f32 v164, v168, v169
	v_cvt_pk_bf16_f32 v165, v224, v225
	v_cvt_pk_bf16_f32 v166, v226, v227
	v_cvt_pk_bf16_f32 v167, v228, v229
	v_add_u32_e32 v234, 0x40000, v232
	global_store_dwordx4 v234, v[164:167], s[24:25]
	s_waitcnt vmcnt(15)
	v_lshlrev_b32_e32 v168, 16, v180
	v_and_b32_e32 v169, 0xffff0000, v180
	v_lshlrev_b32_e32 v224, 16, v181
	v_and_b32_e32 v225, 0xffff0000, v181
	v_lshlrev_b32_e32 v226, 16, v182
	v_and_b32_e32 v227, 0xffff0000, v182
	v_lshlrev_b32_e32 v228, 16, v183
	v_and_b32_e32 v229, 0xffff0000, v183
	v_pk_fma_f32 v[168:169], v[28:29], v[216:217], v[168:169]
	v_pk_fma_f32 v[224:225], v[30:31], v[218:219], v[224:225]
	v_pk_fma_f32 v[226:227], v[24:25], v[220:221], v[226:227]
	v_pk_fma_f32 v[228:229], v[26:27], v[222:223], v[228:229]
	v_cvt_pk_bf16_f32 v180, v168, v169
	v_cvt_pk_bf16_f32 v181, v224, v225
	v_cvt_pk_bf16_f32 v182, v226, v227
	v_cvt_pk_bf16_f32 v183, v228, v229
	v_add_u32_e32 v234, 0x40000, v232
	global_store_dwordx4 v234, v[180:183], s[24:25] offset:256
	s_waitcnt vmcnt(15)
	v_lshlrev_b32_e32 v168, 16, v184
	v_and_b32_e32 v169, 0xffff0000, v184
	v_lshlrev_b32_e32 v224, 16, v185
	v_and_b32_e32 v225, 0xffff0000, v185
	v_lshlrev_b32_e32 v226, 16, v186
	v_and_b32_e32 v227, 0xffff0000, v186
	v_lshlrev_b32_e32 v228, 16, v187
	v_and_b32_e32 v229, 0xffff0000, v187
	v_pk_fma_f32 v[168:169], v[92:93], v[208:209], v[168:169]
	v_pk_fma_f32 v[224:225], v[94:95], v[210:211], v[224:225]
	v_pk_fma_f32 v[226:227], v[88:89], v[212:213], v[226:227]
	v_pk_fma_f32 v[228:229], v[90:91], v[214:215], v[228:229]
	v_cvt_pk_bf16_f32 v184, v168, v169
	v_cvt_pk_bf16_f32 v185, v224, v225
	v_cvt_pk_bf16_f32 v186, v226, v227
	v_cvt_pk_bf16_f32 v187, v228, v229
	v_add_u32_e32 v234, 0x48000, v232
	global_store_dwordx4 v234, v[184:187], s[24:25]
	s_waitcnt vmcnt(15)
; __device__ __forceinline__ u32x4 pack8(const f32x4 a, const f32x4 b) { u32x4 w; w.x = pk2(a[0], a[1]); w.y = pk2(a[2], a[3]); w.z = pk2(b[0], b[1]); w.w = pk2(b[2], b[3]); return w; }
; __device__ __forceinline__ void unpack8(const u32x4 w, f32x4& a, f32x4& b) { a[0] = bflo(w.x); a[1] = bfhi(w.x); a[2] = bflo(w.y); a[3] = bfhi(w.y); b[0] = bflo(w.z); b[1] = bfhi(w.z); b[2] = bflo(w.w); b[3] = bfhi(w.w); }
;     __device__ __forceinline__ bool operator()(EPI_ARGS) const {
;     ...
;                 bf16_t* hp = hbuf + (size_t)u.pm * 256 * D;
; #pragma unroll
;                 for (int ai = 0; ai < 2; ++ai) {
;                     f32x4 r0[4], r1[4];
; #pragma unroll
;                     for (int m = 0; m < 4; ++m) { const size_t o = (size_t)ROWLOC(ai, m) * D + col;
;                         if (RES_BF16) unpack8(*(const u32x4*)(hp + o), r0[m], r1[m]);
;                         else { const float* rp = res_f32 + (size_t)u.pm * 256 * D + o; r0[m] = *(const f32x4*)rp; r1[m] = *(const f32x4*)(rp + 4); } }
; #pragma unroll
;                     for (int m = 0; m < 4; ++m) { const size_t o = (size_t)ROWLOC(ai, m) * D + col;
;                         *(u32x4*)(hp + o) = pack8(r0[m] + g0 * acc[ai][bj][m][0], r1[m] + g1 * acc[ai][bj][m][1]); }
;                 }
	v_lshlrev_b32_e32 v168, 16, v188
	v_and_b32_e32 v169, 0xffff0000, v188
	v_lshlrev_b32_e32 v224, 16, v189
	v_and_b32_e32 v225, 0xffff0000, v189
	v_lshlrev_b32_e32 v226, 16, v190
	v_and_b32_e32 v227, 0xffff0000, v190
	v_lshlrev_b32_e32 v228, 16, v191
	v_and_b32_e32 v229, 0xffff0000, v191
	v_pk_fma_f32 v[168:169], v[20:21], v[216:217], v[168:169]
	v_pk_fma_f32 v[224:225], v[22:23], v[218:219], v[224:225]
	v_pk_fma_f32 v[226:227], v[16:17], v[220:221], v[226:227]
	v_pk_fma_f32 v[228:229], v[18:19], v[222:223], v[228:229]
	v_cvt_pk_bf16_f32 v188, v168, v169
	v_cvt_pk_bf16_f32 v189, v224, v225
	v_cvt_pk_bf16_f32 v190, v226, v227
	v_cvt_pk_bf16_f32 v191, v228, v229
	v_add_u32_e32 v234, 0x48000, v232
	global_store_dwordx4 v234, v[188:191], s[24:25] offset:256
	s_waitcnt vmcnt(15)
	v_lshlrev_b32_e32 v168, 16, v192
	v_and_b32_e32 v169, 0xffff0000, v192
	v_lshlrev_b32_e32 v224, 16, v193
	v_and_b32_e32 v225, 0xffff0000, v193
	v_lshlrev_b32_e32 v226, 16, v194
	v_and_b32_e32 v227, 0xffff0000, v194
	v_lshlrev_b32_e32 v228, 16, v195
	v_and_b32_e32 v229, 0xffff0000, v195
	v_pk_fma_f32 v[168:169], v[80:81], v[208:209], v[168:169]
	v_pk_fma_f32 v[224:225], v[82:83], v[210:211], v[224:225]
	v_pk_fma_f32 v[226:227], v[72:73], v[212:213], v[226:227]
	v_pk_fma_f32 v[228:229], v[74:75], v[214:215], v[228:229]
	v_cvt_pk_bf16_f32 v192, v168, v169
	v_cvt_pk_bf16_f32 v193, v224, v225
	v_cvt_pk_bf16_f32 v194, v226, v227
	v_cvt_pk_bf16_f32 v195, v228, v229
	v_add_u32_e32 v234, 0x50000, v232
	global_store_dwordx4 v234, v[192:195], s[24:25]
	s_waitcnt vmcnt(15)
	v_lshlrev_b32_e32 v168, 16, v196
	v_and_b32_e32 v169, 0xffff0000, v196
	v_lshlrev_b32_e32 v224, 16, v197
	v_and_b32_e32 v225, 0xffff0000, v197
	v_lshlrev_b32_e32 v226, 16, v198
	v_and_b32_e32 v227, 0xffff0000, v198
	v_lshlrev_b32_e32 v228, 16, v199
	v_and_b32_e32 v229, 0xffff0000, v199
	v_pk_fma_f32 v[168:169], v[12:13], v[216:217], v[168:169]
	v_pk_fma_f32 v[224:225], v[14:15], v[218:219], v[224:225]
	v_pk_fma_f32 v[226:227], v[8:9], v[220:221], v[226:227]
	v_pk_fma_f32 v[228:229], v[10:11], v[222:223], v[228:229]
	v_cvt_pk_bf16_f32 v196, v168, v169
	v_cvt_pk_bf16_f32 v197, v224, v225
	v_cvt_pk_bf16_f32 v198, v226, v227
	v_cvt_pk_bf16_f32 v199, v228, v229
	v_add_u32_e32 v234, 0x50000, v232
	global_store_dwordx4 v234, v[196:199], s[24:25] offset:256
	s_waitcnt vmcnt(15)
	v_lshlrev_b32_e32 v168, 16, v200
	v_and_b32_e32 v169, 0xffff0000, v200
	v_lshlrev_b32_e32 v224, 16, v201
	v_and_b32_e32 v225, 0xffff0000, v201
	v_lshlrev_b32_e32 v226, 16, v202
	v_and_b32_e32 v227, 0xffff0000, v202
	v_lshlrev_b32_e32 v228, 16, v203
	v_and_b32_e32 v229, 0xffff0000, v203
	v_pk_fma_f32 v[168:169], v[68:69], v[208:209], v[168:169]
	v_pk_fma_f32 v[224:225], v[70:71], v[210:211], v[224:225]
	v_pk_fma_f32 v[226:227], v[64:65], v[212:213], v[226:227]
	v_pk_fma_f32 v[228:229], v[66:67], v[214:215], v[228:229]
	v_cvt_pk_bf16_f32 v200, v168, v169
	v_cvt_pk_bf16_f32 v201, v224, v225
	v_cvt_pk_bf16_f32 v202, v226, v227
	v_cvt_pk_bf16_f32 v203, v228, v229
	v_add_u32_e32 v234, 0x58000, v232
	global_store_dwordx4 v234, v[200:203], s[24:25]
	s_waitcnt vmcnt(15)
	v_lshlrev_b32_e32 v168, 16, v204
	v_and_b32_e32 v169, 0xffff0000, v204
	v_lshlrev_b32_e32 v224, 16, v205
	v_and_b32_e32 v225, 0xffff0000, v205
	v_lshlrev_b32_e32 v226, 16, v206
	v_and_b32_e32 v227, 0xffff0000, v206
	v_lshlrev_b32_e32 v228, 16, v207
	v_and_b32_e32 v229, 0xffff0000, v207
	v_pk_fma_f32 v[168:169], v[4:5], v[216:217], v[168:169]
	v_pk_fma_f32 v[224:225], v[6:7], v[218:219], v[224:225]
	v_pk_fma_f32 v[226:227], v[0:1], v[220:221], v[226:227]
	v_pk_fma_f32 v[228:229], v[2:3], v[222:223], v[228:229]
	v_cvt_pk_bf16_f32 v204, v168, v169
	v_cvt_pk_bf16_f32 v205, v224, v225
	v_cvt_pk_bf16_f32 v206, v226, v227
	v_cvt_pk_bf16_f32 v207, v228, v229
	v_add_u32_e32 v234, 0x58000, v232
	global_store_dwordx4 v234, v[204:207], s[24:25] offset:256
	s_andn2_b64 vcc, exec, s[8:9]
	s_mov_b64 s[8:9], -1
	s_cbranch_vccnz .LBB0_1344
	s_andn2_b64 vcc, exec, s[10:11]
	s_cbranch_vccnz .LBB0_1343
	s_barrier
	s_branch .LBB0_1343

; __device__ __forceinline__ u32x4 pack8(const f32x4 a, const f32x4 b) { u32x4 w; w.x = pk2(a[0], a[1]); w.y = pk2(a[2], a[3]); w.z = pk2(b[0], b[1]); w.w = pk2(b[2], b[3]); return w; }
; __device__ __forceinline__ void unpack8(const u32x4 w, f32x4& a, f32x4& b) { a[0] = bflo(w.x); a[1] = bfhi(w.x); a[2] = bflo(w.y); a[3] = bfhi(w.y); b[0] = bflo(w.z); b[1] = bfhi(w.z); b[2] = bflo(w.w); b[3] = bfhi(w.w); }
;     __device__ __forceinline__ bool operator()(EPI_ARGS) const {
;         const int ms = u.pm < 64 ? 0 : (u.pm < 128 ? 1 : 2);
;         const float* g = mods + ms * (NMOD * D) + gidx * D;
; #pragma unroll
;         for (int bj = 0; bj < 2; ++bj) {
;             const int col = u.pn * 256 + COLLOC(bj);
;             const f32x4 g0 = *(const f32x4*)(g + col) * coef, g1 = *(const f32x4*)(g + col + 4) * coef;
;             if (u.kind == 1) {
;                 float* dst = dst_ctx + (size_t)(u.pm - 128) * 256 * D;
; #pragma unroll
;                 for (int ai = 0; ai < 2; ++ai)
; #pragma unroll
;                     for (int m = 0; m < 4; ++m) {
;                         float* sl = dst + (size_t)u.w * (TC * D) + (size_t)ROWLOC(ai, m) * D + col;
;                         *(f32x4*)sl = g0 * acc[ai][bj][m][0]; *(f32x4*)(sl + 4) = g1 * acc[ai][bj][m][1];
;                     }
;             } else {
;                 bf16_t* hp = hbuf + (size_t)u.pm * 256 * D;
; #pragma unroll
;                 for (int ai = 0; ai < 2; ++ai) {
;                     f32x4 r0[4], r1[4];
; #pragma unroll
;                     for (int m = 0; m < 4; ++m) { const size_t o = (size_t)ROWLOC(ai, m) * D + col;
;                         if (RES_BF16) unpack8(*(const u32x4*)(hp + o), r0[m], r1[m]);
;                         else { const float* rp = res_f32 + (size_t)u.pm * 256 * D + o; r0[m] = *(const f32x4*)rp; r1[m] = *(const f32x4*)(rp + 4); } }
; #pragma unroll
;                     for (int m = 0; m < 4; ++m) { const size_t o = (size_t)ROWLOC(ai, m) * D + col;
;                         *(u32x4*)(hp + o) = pack8(r0[m] + g0 * acc[ai][bj][m][0], r1[m] + g1 * acc[ai][bj][m][1]); }
;                 }
.LBB0_1568:
	s_cmpk_lt_i32 s16, 0x80
	s_cselect_b32 s17, s56, 0x4800
	s_cmp_gt_i32 s16, 63
	s_cselect_b32 s17, s17, 0
	s_lshl_b32 s17, s17, 2
	s_add_u32 s17, s8, s17
	s_addc_u32 s23, s9, 0
	s_add_u32 s22, s17, 0x3d08000
	s_addc_u32 s23, s23, 0
	s_lshl_b32 s17, s58, 8
	s_or_b32 s17, s17, s47
	s_lshl_b32 s24, s16, 19
	v_lshl_add_u32 v230, v178, 3, s17
	s_add_u32 s24, s44, s24
	v_add_u32_e32 v231, s46, v177
	s_addc_u32 s25, s45, 0
	v_lshlrev_b32_e32 v233, 2, v230
	v_lshlrev_b32_e32 v230, 1, v230
	v_lshl_add_u32 v232, v231, 11, v230
	global_load_dwordx4 v[208:211], v233, s[22:23]
	global_load_dwordx4 v[212:215], v233, s[22:23] offset:16
	global_load_dwordx4 v[216:219], v233, s[22:23] offset:512
	global_load_dwordx4 v[220:223], v233, s[22:23] offset:528
	global_load_dwordx4 v[128:131], v232, s[24:25]
	global_load_dwordx4 v[132:135], v232, s[24:25] offset:256
	v_add_u32_e32 v234, 0x8000, v232
	global_load_dwordx4 v[136:139], v234, s[24:25]
	global_load_dwordx4 v[140:143], v234, s[24:25] offset:256
	v_add_u32_e32 v234, 0x10000, v232
	global_load_dwordx4 v[152:155], v234, s[24:25]
	global_load_dwordx4 v[156:159], v234, s[24:25] offset:256
	v_add_u32_e32 v234, 0x18000, v232
	global_load_dwordx4 v[160:163], v234, s[24:25]
	global_load_dwordx4 v[164:167], v234, s[24:25] offset:256
	v_add_u32_e32 v234, 0x40000, v232
	global_load_dwordx4 v[168:171], v234, s[24:25]
	global_load_dwordx4 v[172:175], v234, s[24:25] offset:256
	v_add_u32_e32 v234, 0x48000, v232
	global_load_dwordx4 v[184:187], v234, s[24:25]
	global_load_dwordx4 v[188:191], v234, s[24:25] offset:256
	v_add_u32_e32 v234, 0x50000, v232
	global_load_dwordx4 v[192:195], v234, s[24:25]
	global_load_dwordx4 v[196:199], v234, s[24:25] offset:256
	v_add_u32_e32 v234, 0x58000, v232
	global_load_dwordx4 v[200:203], v234, s[24:25]
	global_load_dwordx4 v[204:207], v234, s[24:25] offset:256
	s_waitcnt vmcnt(15)
	v_pk_mul_f32 v[208:209], v[208:209], 0.5 op_sel_hi:[1,0]
	v_pk_mul_f32 v[210:211], v[210:211], 0.5 op_sel_hi:[1,0]
	v_pk_mul_f32 v[212:213], v[212:213], 0.5 op_sel_hi:[1,0]
	v_pk_mul_f32 v[214:215], v[214:215], 0.5 op_sel_hi:[1,0]
	v_pk_mul_f32 v[216:217], v[216:217], 0.5 op_sel_hi:[1,0]
	v_pk_mul_f32 v[218:219], v[218:219], 0.5 op_sel_hi:[1,0]
	v_pk_mul_f32 v[220:221], v[220:221], 0.5 op_sel_hi:[1,0]
	v_pk_mul_f32 v[222:223], v[222:223], 0.5 op_sel_hi:[1,0]
	v_lshlrev_b32_e32 v150, 16, v128
	v_and_b32_e32 v151, 0xffff0000, v128
	v_lshlrev_b32_e32 v224, 16, v129
	v_and_b32_e32 v225, 0xffff0000, v129
	v_lshlrev_b32_e32 v226, 16, v130
	v_and_b32_e32 v227, 0xffff0000, v130
	v_lshlrev_b32_e32 v228, 16, v131
	v_and_b32_e32 v229, 0xffff0000, v131
	v_pk_fma_f32 v[150:151], v[124:125], v[208:209], v[150:151]
	v_pk_fma_f32 v[224:225], v[126:127], v[210:211], v[224:225]
	v_pk_fma_f32 v[226:227], v[120:121], v[212:213], v[226:227]
	v_pk_fma_f32 v[228:229], v[122:123], v[214:215], v[228:229]
	v_cvt_pk_bf16_f32 v128, v150, v151
	v_cvt_pk_bf16_f32 v129, v224, v225
	v_cvt_pk_bf16_f32 v130, v226, v227
	v_cvt_pk_bf16_f32 v131, v228, v229
	global_store_dwordx4 v232, v[128:131], s[24:25]
	s_waitcnt vmcnt(15)
	v_lshlrev_b32_e32 v150, 16, v132
	v_and_b32_e32 v151, 0xffff0000, v132
	v_lshlrev_b32_e32 v224, 16, v133
	v_and_b32_e32 v225, 0xffff0000, v133
	v_lshlrev_b32_e32 v226, 16, v134
	v_and_b32_e32 v227, 0xffff0000, v134
	v_lshlrev_b32_e32 v228, 16, v135
	v_and_b32_e32 v229, 0xffff0000, v135
	v_pk_fma_f32 v[150:151], v[60:61], v[216:217], v[150:151]
	v_pk_fma_f32 v[224:225], v[62:63], v[218:219], v[224:225]
	v_pk_fma_f32 v[226:227], v[56:57], v[220:221], v[226:227]
	v_pk_fma_f32 v[228:229], v[58:59], v[222:223], v[228:229]
	v_cvt_pk_bf16_f32 v132, v150, v151
	v_cvt_pk_bf16_f32 v133, v224, v225
	v_cvt_pk_bf16_f32 v134, v226, v227
	v_cvt_pk_bf16_f32 v135, v228, v229
	global_store_dwordx4 v232, v[132:135], s[24:25] offset:256
	s_waitcnt vmcnt(15)
	v_lshlrev_b32_e32 v150, 16, v136
	v_and_b32_e32 v151, 0xffff0000, v136
	v_lshlrev_b32_e32 v224, 16, v137
	v_and_b32_e32 v225, 0xffff0000, v137
	v_lshlrev_b32_e32 v226, 16, v138
	v_and_b32_e32 v227, 0xffff0000, v138
	v_lshlrev_b32_e32 v228, 16, v139
	v_and_b32_e32 v229, 0xffff0000, v139
	v_pk_fma_f32 v[150:151], v[116:117], v[208:209], v[150:151]
	v_pk_fma_f32 v[224:225], v[118:119], v[210:211], v[224:225]
	v_pk_fma_f32 v[226:227], v[112:113], v[212:213], v[226:227]
	v_pk_fma_f32 v[228:229], v[114:115], v[214:215], v[228:229]
	v_cvt_pk_bf16_f32 v136, v150, v151
	v_cvt_pk_bf16_f32 v137, v224, v225
	v_cvt_pk_bf16_f32 v138, v226, v227
	v_cvt_pk_bf16_f32 v139, v228, v229
	v_add_u32_e32 v234, 0x8000, v232
	global_store_dwordx4 v234, v[136:139], s[24:25]
	s_waitcnt vmcnt(15)
	v_lshlrev_b32_e32 v150, 16, v140
	v_and_b32_e32 v151, 0xffff0000, v140
	v_lshlrev_b32_e32 v224, 16, v141
	v_and_b32_e32 v225, 0xffff0000, v141
	v_lshlrev_b32_e32 v226, 16, v142
	v_and_b32_e32 v227, 0xffff0000, v142
	v_lshlrev_b32_e32 v228, 16, v143
	v_and_b32_e32 v229, 0xffff0000, v143
	v_pk_fma_f32 v[150:151], v[52:53], v[216:217], v[150:151]
	v_pk_fma_f32 v[224:225], v[54:55], v[218:219], v[224:225]
	v_pk_fma_f32 v[226:227], v[48:49], v[220:221], v[226:227]
	v_pk_fma_f32 v[228:229], v[50:51], v[222:223], v[228:229]
	v_cvt_pk_bf16_f32 v140, v150, v151
	v_cvt_pk_bf16_f32 v141, v224, v225
	v_cvt_pk_bf16_f32 v142, v226, v227
	v_cvt_pk_bf16_f32 v143, v228, v229
	v_add_u32_e32 v234, 0x8000, v232
	global_store_dwordx4 v234, v[140:143], s[24:25] offset:256
	s_waitcnt vmcnt(15)
; __device__ __forceinline__ u32x4 pack8(const f32x4 a, const f32x4 b) { u32x4 w; w.x = pk2(a[0], a[1]); w.y = pk2(a[2], a[3]); w.z = pk2(b[0], b[1]); w.w = pk2(b[2], b[3]); return w; }
; __device__ __forceinline__ void unpack8(const u32x4 w, f32x4& a, f32x4& b) { a[0] = bflo(w.x); a[1] = bfhi(w.x); a[2] = bflo(w.y); a[3] = bfhi(w.y); b[0] = bflo(w.z); b[1] = bfhi(w.z); b[2] = bflo(w.w); b[3] = bfhi(w.w); }
;     __device__ __forceinline__ bool operator()(EPI_ARGS) const {
;     ...
;                 bf16_t* hp = hbuf + (size_t)u.pm * 256 * D;
; #pragma unroll
;                 for (int ai = 0; ai < 2; ++ai) {
;                     f32x4 r0[4], r1[4];
; #pragma unroll
;                     for (int m = 0; m < 4; ++m) { const size_t o = (size_t)ROWLOC(ai, m) * D + col;
;                         if (RES_BF16) unpack8(*(const u32x4*)(hp + o), r0[m], r1[m]);
;                         else { const float* rp = res_f32 + (size_t)u.pm * 256 * D + o; r0[m] = *(const f32x4*)rp; r1[m] = *(const f32x4*)(rp + 4); } }
; #pragma unroll
;                     for (int m = 0; m < 4; ++m) { const size_t o = (size_t)ROWLOC(ai, m) * D + col;
;                         *(u32x4*)(hp + o) = pack8(r0[m] + g0 * acc[ai][bj][m][0], r1[m] + g1 * acc[ai][bj][m][1]); }
;                 }
	v_lshlrev_b32_e32 v150, 16, v152
	v_and_b32_e32 v151, 0xffff0000, v152
	v_lshlrev_b32_e32 v224, 16, v153
	v_and_b32_e32 v225, 0xffff0000, v153
	v_lshlrev_b32_e32 v226, 16, v154
	v_and_b32_e32 v227, 0xffff0000, v154
	v_lshlrev_b32_e32 v228, 16, v155
	v_and_b32_e32 v229, 0xffff0000, v155
	v_pk_fma_f32 v[150:151], v[108:109], v[208:209], v[150:151]
	v_pk_fma_f32 v[224:225], v[110:111], v[210:211], v[224:225]
	v_pk_fma_f32 v[226:227], v[104:105], v[212:213], v[226:227]
	v_pk_fma_f32 v[228:229], v[106:107], v[214:215], v[228:229]
	v_cvt_pk_bf16_f32 v152, v150, v151
	v_cvt_pk_bf16_f32 v153, v224, v225
	v_cvt_pk_bf16_f32 v154, v226, v227
	v_cvt_pk_bf16_f32 v155, v228, v229
	v_add_u32_e32 v234, 0x10000, v232
	global_store_dwordx4 v234, v[152:155], s[24:25]
	s_waitcnt vmcnt(15)
	v_lshlrev_b32_e32 v150, 16, v156
	v_and_b32_e32 v151, 0xffff0000, v156
	v_lshlrev_b32_e32 v224, 16, v157
	v_and_b32_e32 v225, 0xffff0000, v157
	v_lshlrev_b32_e32 v226, 16, v158
	v_and_b32_e32 v227, 0xffff0000, v158
	v_lshlrev_b32_e32 v228, 16, v159
	v_and_b32_e32 v229, 0xffff0000, v159
	v_pk_fma_f32 v[150:151], v[44:45], v[216:217], v[150:151]
	v_pk_fma_f32 v[224:225], v[46:47], v[218:219], v[224:225]
	v_pk_fma_f32 v[226:227], v[40:41], v[220:221], v[226:227]
	v_pk_fma_f32 v[228:229], v[42:43], v[222:223], v[228:229]
	v_cvt_pk_bf16_f32 v156, v150, v151
	v_cvt_pk_bf16_f32 v157, v224, v225
	v_cvt_pk_bf16_f32 v158, v226, v227
	v_cvt_pk_bf16_f32 v159, v228, v229
	v_add_u32_e32 v234, 0x10000, v232
	global_store_dwordx4 v234, v[156:159], s[24:25] offset:256
	s_waitcnt vmcnt(15)
	v_lshlrev_b32_e32 v150, 16, v160
	v_and_b32_e32 v151, 0xffff0000, v160
	v_lshlrev_b32_e32 v224, 16, v161
	v_and_b32_e32 v225, 0xffff0000, v161
	v_lshlrev_b32_e32 v226, 16, v162
	v_and_b32_e32 v227, 0xffff0000, v162
	v_lshlrev_b32_e32 v228, 16, v163
	v_and_b32_e32 v229, 0xffff0000, v163
	v_pk_fma_f32 v[150:151], v[100:101], v[208:209], v[150:151]
	v_pk_fma_f32 v[224:225], v[102:103], v[210:211], v[224:225]
	v_pk_fma_f32 v[226:227], v[96:97], v[212:213], v[226:227]
	v_pk_fma_f32 v[228:229], v[98:99], v[214:215], v[228:229]
	v_cvt_pk_bf16_f32 v160, v150, v151
	v_cvt_pk_bf16_f32 v161, v224, v225
	v_cvt_pk_bf16_f32 v162, v226, v227
	v_cvt_pk_bf16_f32 v163, v228, v229
	v_add_u32_e32 v234, 0x18000, v232
	global_store_dwordx4 v234, v[160:163], s[24:25]
	s_waitcnt vmcnt(15)
	v_lshlrev_b32_e32 v150, 16, v164
	v_and_b32_e32 v151, 0xffff0000, v164
	v_lshlrev_b32_e32 v224, 16, v165
	v_and_b32_e32 v225, 0xffff0000, v165
	v_lshlrev_b32_e32 v226, 16, v166
	v_and_b32_e32 v227, 0xffff0000, v166
	v_lshlrev_b32_e32 v228, 16, v167
	v_and_b32_e32 v229, 0xffff0000, v167
	v_pk_fma_f32 v[150:151], v[36:37], v[216:217], v[150:151]
	v_pk_fma_f32 v[224:225], v[38:39], v[218:219], v[224:225]
	v_pk_fma_f32 v[226:227], v[32:33], v[220:221], v[226:227]
	v_pk_fma_f32 v[228:229], v[34:35], v[222:223], v[228:229]
	v_cvt_pk_bf16_f32 v164, v150, v151
	v_cvt_pk_bf16_f32 v165, v224, v225
	v_cvt_pk_bf16_f32 v166, v226, v227
	v_cvt_pk_bf16_f32 v167, v228, v229
	v_add_u32_e32 v234, 0x18000, v232
	global_store_dwordx4 v234, v[164:167], s[24:25] offset:256
	s_waitcnt vmcnt(15)
	v_lshlrev_b32_e32 v150, 16, v168
	v_and_b32_e32 v151, 0xffff0000, v168
	v_lshlrev_b32_e32 v224, 16, v169
	v_and_b32_e32 v225, 0xffff0000, v169
	v_lshlrev_b32_e32 v226, 16, v170
	v_and_b32_e32 v227, 0xffff0000, v170
	v_lshlrev_b32_e32 v228, 16, v171
	v_and_b32_e32 v229, 0xffff0000, v171
	v_pk_fma_f32 v[150:151], v[92:93], v[208:209], v[150:151]
	v_pk_fma_f32 v[224:225], v[94:95], v[210:211], v[224:225]
	v_pk_fma_f32 v[226:227], v[88:89], v[212:213], v[226:227]
	v_pk_fma_f32 v[228:229], v[90:91], v[214:215], v[228:229]
	v_cvt_pk_bf16_f32 v168, v150, v151
	v_cvt_pk_bf16_f32 v169, v224, v225
	v_cvt_pk_bf16_f32 v170, v226, v227
	v_cvt_pk_bf16_f32 v171, v228, v229
	v_add_u32_e32 v234, 0x40000, v232
	global_store_dwordx4 v234, v[168:171], s[24:25]
	s_waitcnt vmcnt(15)
	v_lshlrev_b32_e32 v150, 16, v172
	v_and_b32_e32 v151, 0xffff0000, v172
	v_lshlrev_b32_e32 v224, 16, v173
	v_and_b32_e32 v225, 0xffff0000, v173
	v_lshlrev_b32_e32 v226, 16, v174
	v_and_b32_e32 v227, 0xffff0000, v174
	v_lshlrev_b32_e32 v228, 16, v175
	v_and_b32_e32 v229, 0xffff0000, v175
	v_pk_fma_f32 v[150:151], v[28:29], v[216:217], v[150:151]
	v_pk_fma_f32 v[224:225], v[30:31], v[218:219], v[224:225]
	v_pk_fma_f32 v[226:227], v[24:25], v[220:221], v[226:227]
	v_pk_fma_f32 v[228:229], v[26:27], v[222:223], v[228:229]
	v_cvt_pk_bf16_f32 v172, v150, v151
	v_cvt_pk_bf16_f32 v173, v224, v225
	v_cvt_pk_bf16_f32 v174, v226, v227
	v_cvt_pk_bf16_f32 v175, v228, v229
	v_add_u32_e32 v234, 0x40000, v232
	global_store_dwordx4 v234, v[172:175], s[24:25] offset:256
	s_waitcnt vmcnt(15)
; __device__ __forceinline__ u32x4 pack8(const f32x4 a, const f32x4 b) { u32x4 w; w.x = pk2(a[0], a[1]); w.y = pk2(a[2], a[3]); w.z = pk2(b[0], b[1]); w.w = pk2(b[2], b[3]); return w; }
; __device__ __forceinline__ void unpack8(const u32x4 w, f32x4& a, f32x4& b) { a[0] = bflo(w.x); a[1] = bfhi(w.x); a[2] = bflo(w.y); a[3] = bfhi(w.y); b[0] = bflo(w.z); b[1] = bfhi(w.z); b[2] = bflo(w.w); b[3] = bfhi(w.w); }
;     __device__ __forceinline__ bool operator()(EPI_ARGS) const {
;     ...
;                 bf16_t* hp = hbuf + (size_t)u.pm * 256 * D;
; #pragma unroll
;                 for (int ai = 0; ai < 2; ++ai) {
;                     f32x4 r0[4], r1[4];
; #pragma unroll
;                     for (int m = 0; m < 4; ++m) { const size_t o = (size_t)ROWLOC(ai, m) * D + col;
;                         if (RES_BF16) unpack8(*(const u32x4*)(hp + o), r0[m], r1[m]);
;                         else { const float* rp = res_f32 + (size_t)u.pm * 256 * D + o; r0[m] = *(const f32x4*)rp; r1[m] = *(const f32x4*)(rp + 4); } }
; #pragma unroll
;                     for (int m = 0; m < 4; ++m) { const size_t o = (size_t)ROWLOC(ai, m) * D + col;
;                         *(u32x4*)(hp + o) = pack8(r0[m] + g0 * acc[ai][bj][m][0], r1[m] + g1 * acc[ai][bj][m][1]); }
;                 }
	v_lshlrev_b32_e32 v150, 16, v184
	v_and_b32_e32 v151, 0xffff0000, v184
	v_lshlrev_b32_e32 v224, 16, v185
	v_and_b32_e32 v225, 0xffff0000, v185
	v_lshlrev_b32_e32 v226, 16, v186
	v_and_b32_e32 v227, 0xffff0000, v186
	v_lshlrev_b32_e32 v228, 16, v187
	v_and_b32_e32 v229, 0xffff0000, v187
	v_pk_fma_f32 v[150:151], v[84:85], v[208:209], v[150:151]
	v_pk_fma_f32 v[224:225], v[86:87], v[210:211], v[224:225]
	v_pk_fma_f32 v[226:227], v[80:81], v[212:213], v[226:227]
	v_pk_fma_f32 v[228:229], v[82:83], v[214:215], v[228:229]
	v_cvt_pk_bf16_f32 v184, v150, v151
	v_cvt_pk_bf16_f32 v185, v224, v225
	v_cvt_pk_bf16_f32 v186, v226, v227
	v_cvt_pk_bf16_f32 v187, v228, v229
	v_add_u32_e32 v234, 0x48000, v232
	global_store_dwordx4 v234, v[184:187], s[24:25]
	s_waitcnt vmcnt(15)
	v_lshlrev_b32_e32 v150, 16, v188
	v_and_b32_e32 v151, 0xffff0000, v188
	v_lshlrev_b32_e32 v224, 16, v189
	v_and_b32_e32 v225, 0xffff0000, v189
	v_lshlrev_b32_e32 v226, 16, v190
	v_and_b32_e32 v227, 0xffff0000, v190
	v_lshlrev_b32_e32 v228, 16, v191
	v_and_b32_e32 v229, 0xffff0000, v191
	v_pk_fma_f32 v[150:151], v[20:21], v[216:217], v[150:151]
	v_pk_fma_f32 v[224:225], v[22:23], v[218:219], v[224:225]
	v_pk_fma_f32 v[226:227], v[16:17], v[220:221], v[226:227]
	v_pk_fma_f32 v[228:229], v[18:19], v[222:223], v[228:229]
	v_cvt_pk_bf16_f32 v188, v150, v151
	v_cvt_pk_bf16_f32 v189, v224, v225
	v_cvt_pk_bf16_f32 v190, v226, v227
	v_cvt_pk_bf16_f32 v191, v228, v229
	v_add_u32_e32 v234, 0x48000, v232
	global_store_dwordx4 v234, v[188:191], s[24:25] offset:256
	s_waitcnt vmcnt(15)
	v_lshlrev_b32_e32 v150, 16, v192
	v_and_b32_e32 v151, 0xffff0000, v192
	v_lshlrev_b32_e32 v224, 16, v193
	v_and_b32_e32 v225, 0xffff0000, v193
	v_lshlrev_b32_e32 v226, 16, v194
	v_and_b32_e32 v227, 0xffff0000, v194
	v_lshlrev_b32_e32 v228, 16, v195
	v_and_b32_e32 v229, 0xffff0000, v195
	v_pk_fma_f32 v[150:151], v[76:77], v[208:209], v[150:151]
	v_pk_fma_f32 v[224:225], v[78:79], v[210:211], v[224:225]
	v_pk_fma_f32 v[226:227], v[72:73], v[212:213], v[226:227]
	v_pk_fma_f32 v[228:229], v[74:75], v[214:215], v[228:229]
	v_cvt_pk_bf16_f32 v192, v150, v151
	v_cvt_pk_bf16_f32 v193, v224, v225
	v_cvt_pk_bf16_f32 v194, v226, v227
	v_cvt_pk_bf16_f32 v195, v228, v229
	v_add_u32_e32 v234, 0x50000, v232
	global_store_dwordx4 v234, v[192:195], s[24:25]
	s_waitcnt vmcnt(15)
	v_lshlrev_b32_e32 v150, 16, v196
	v_and_b32_e32 v151, 0xffff0000, v196
	v_lshlrev_b32_e32 v224, 16, v197
	v_and_b32_e32 v225, 0xffff0000, v197
	v_lshlrev_b32_e32 v226, 16, v198
	v_and_b32_e32 v227, 0xffff0000, v198
	v_lshlrev_b32_e32 v228, 16, v199
	v_and_b32_e32 v229, 0xffff0000, v199
	v_pk_fma_f32 v[150:151], v[12:13], v[216:217], v[150:151]
	v_pk_fma_f32 v[224:225], v[14:15], v[218:219], v[224:225]
	v_pk_fma_f32 v[226:227], v[8:9], v[220:221], v[226:227]
	v_pk_fma_f32 v[228:229], v[10:11], v[222:223], v[228:229]
	v_cvt_pk_bf16_f32 v196, v150, v151
	v_cvt_pk_bf16_f32 v197, v224, v225
	v_cvt_pk_bf16_f32 v198, v226, v227
	v_cvt_pk_bf16_f32 v199, v228, v229
	v_add_u32_e32 v234, 0x50000, v232
	global_store_dwordx4 v234, v[196:199], s[24:25] offset:256
	s_waitcnt vmcnt(15)
	v_lshlrev_b32_e32 v150, 16, v200
	v_and_b32_e32 v151, 0xffff0000, v200
	v_lshlrev_b32_e32 v224, 16, v201
	v_and_b32_e32 v225, 0xffff0000, v201
	v_lshlrev_b32_e32 v226, 16, v202
	v_and_b32_e32 v227, 0xffff0000, v202
	v_lshlrev_b32_e32 v228, 16, v203
	v_and_b32_e32 v229, 0xffff0000, v203
	v_pk_fma_f32 v[150:151], v[68:69], v[208:209], v[150:151]
	v_pk_fma_f32 v[224:225], v[70:71], v[210:211], v[224:225]
	v_pk_fma_f32 v[226:227], v[64:65], v[212:213], v[226:227]
	v_pk_fma_f32 v[228:229], v[66:67], v[214:215], v[228:229]
	v_cvt_pk_bf16_f32 v200, v150, v151
	v_cvt_pk_bf16_f32 v201, v224, v225
	v_cvt_pk_bf16_f32 v202, v226, v227
	v_cvt_pk_bf16_f32 v203, v228, v229
	v_add_u32_e32 v234, 0x58000, v232
	global_store_dwordx4 v234, v[200:203], s[24:25]
	s_waitcnt vmcnt(15)
	v_lshlrev_b32_e32 v150, 16, v204
	v_and_b32_e32 v151, 0xffff0000, v204
	v_lshlrev_b32_e32 v224, 16, v205
	v_and_b32_e32 v225, 0xffff0000, v205
	v_lshlrev_b32_e32 v226, 16, v206
	v_and_b32_e32 v227, 0xffff0000, v206
	v_lshlrev_b32_e32 v228, 16, v207
	v_and_b32_e32 v229, 0xffff0000, v207
	v_pk_fma_f32 v[150:151], v[4:5], v[216:217], v[150:151]
	v_pk_fma_f32 v[224:225], v[6:7], v[218:219], v[224:225]
	v_pk_fma_f32 v[226:227], v[0:1], v[220:221], v[226:227]
	v_pk_fma_f32 v[228:229], v[2:3], v[222:223], v[228:229]
	v_cvt_pk_bf16_f32 v204, v150, v151
	v_cvt_pk_bf16_f32 v205, v224, v225
	v_cvt_pk_bf16_f32 v206, v226, v227
	v_cvt_pk_bf16_f32 v207, v228, v229
	v_add_u32_e32 v234, 0x58000, v232
	global_store_dwordx4 v234, v[204:207], s[24:25] offset:256
	s_andn2_b64 vcc, exec, s[6:7]
	s_mov_b64 s[6:7], -1
	s_cbranch_vccnz .LBB0_1551
	s_andn2_b64 vcc, exec, s[10:11]
	s_cbranch_vccnz .LBB0_1550
	s_barrier
	s_branch .LBB0_1550
